# v36 + dword-load hoists in the G2-u / G2-v / M2 / M4 GEMM epilogues (ssq and bias loads issued early)
# speedup vs baseline: 1.0156x; 1.0039x over previous
; __device__ __forceinline__ unsigned cvt_pk_bf16(float lo, float hi) { unsigned r; asm volatile("v_cvt_pk_bf16_f32 %0, %1, %2" : "=v"(r) : "v"(lo), "v"(hi)); return r; }
; __device__ __forceinline__ f32x2 gelu_pk(f32x2 v) {
;     const f32x2 av = __builtin_elementwise_abs(v), d = av * 0.2316418882f + 1.0f;
;     f32x2 t; t.x = __builtin_amdgcn_rcpf(d.x); t.y = __builtin_amdgcn_rcpf(d.y);
;     f32x2 q = t * 0.5307027145f + (-0.7265760135f); q = q * t + 0.7107068705f; q = q * t + (-0.142248368f); q = q * t + 0.127414796f; q = q * t;
;     const f32x2 s = (v * v) * (-0.72134752044f);
;     f32x2 e; e.x = __builtin_amdgcn_exp2f(s.x); e.y = __builtin_amdgcn_exp2f(s.y);
;     const f32x2 m = v * (q * e), r = v - m;
;     f32x2 o; o.x = v.x < 0.f ? m.x : r.x; o.y = v.y < 0.f ? m.y : r.y; return o;
; }
;     __device__ __forceinline__ void operator()(const f32x4 (&acc)[2][2][4][2], const Unit& u, int wr, int wc, int fr, int fq) const {
;     ...
;             for (int m = 0; m < 4; ++m) { bf16_t* rowp = O + (size_t)(row0 + ai * HALF + m * 16) * ldc + col0;
;                 const float rr = fused ? __builtin_amdgcn_rsqf(ssq[row0 + ai * HALF + m * 16] * inv_n + EPS) : 1.f;
; #pragma unroll
;                 for (int bj = 0; bj < 2; ++bj) { const f32x4 v0 = act4(acc[ai][bj][m][0] * rr + bv[bj][0], ACT), v1 = act4(acc[ai][bj][m][1] * rr + bv[bj][1], ACT);
;                     u32x4 w; w.x = cvt_pk_bf16(v0[0], v0[1]); w.y = cvt_pk_bf16(v0[2], v0[3]); w.z = cvt_pk_bf16(v1[0], v1[1]); w.w = cvt_pk_bf16(v1[2], v1[3]);
;                     *(u32x4*)(rowp + bj * 32) = w; } }
.LBB0_286:
	v_lshl_add_u32 v156, s24, 8, v159
	v_cndmask_b32_e64 v160, 0, 1, s[26:27]
	v_ashrrev_i32_e32 v157, 31, v156
	v_mov_b32_e32 v158, 1.0
	v_cmp_ne_u32_e64 s[8:9], 1, v160
	s_andn2_b64 vcc, exec, s[26:27]
	v_mov_b32_e32 v162, 1.0
	s_cbranch_vccnz .LBB0_288
	v_lshl_add_u64 v[160:161], v[156:157], 2, s[54:55]
	global_load_dword v251, v[160:161], off offset:64
	global_load_dword v250, v[160:161], off offset:128
	global_load_dword v249, v[160:161], off offset:192
	global_load_dword v248, v[160:161], off offset:512
	global_load_dword v247, v[160:161], off offset:576
	global_load_dword v246, v[160:161], off offset:640
	global_load_dword v245, v[160:161], off offset:704
	global_load_dword v160, v[160:161], off
	s_waitcnt vmcnt(0)
	v_fmamk_f32 v160, v160, 0x3a800000, v189
	v_rsq_f32_e32 v162, v160
.LBB0_288:
	s_waitcnt vmcnt(0)
	v_pk_fma_f32 v[166:167], v[140:141], v[162:163], v[44:45] op_sel_hi:[1,0,1]
	v_pk_fma_f32 v[142:143], v[142:143], v[162:163], v[46:47] op_sel_hi:[1,0,1]
	v_and_b32_e32 v141, 0x7fffffff, v167
	v_and_b32_e32 v140, 0x7fffffff, v166
	v_pk_fma_f32 v[140:141], v[140:141], s[82:83], 1.0 op_sel_hi:[1,0,0]
	v_pk_mul_f32 v[174:175], v[166:167], v[166:167]
	v_rcp_f32_e32 v168, v140
	v_rcp_f32_e32 v169, v141
	v_mov_b64_e32 v[140:141], s[70:71]
	v_pk_mul_f32 v[174:175], v[174:175], s[94:95] op_sel_hi:[1,0]
	v_cmp_gt_f32_e32 vcc, 0, v166
	v_pk_fma_f32 v[170:171], v[168:169], s[84:85], v[140:141] op_sel_hi:[1,0,0]
	v_exp_f32_e32 v174, v174
	v_pk_fma_f32 v[170:171], v[168:169], v[170:171], s[88:89] op_sel_hi:[1,1,0]
	v_exp_f32_e32 v175, v175
	v_pk_fma_f32 v[170:171], v[168:169], v[170:171], s[90:91] op_sel_hi:[1,1,0]
	v_lshlrev_b64 v[160:161], 12, v[156:157]
	v_pk_fma_f32 v[170:171], v[168:169], v[170:171], s[92:93] op_sel_hi:[1,1,0]
	v_pk_fma_f32 v[136:137], v[136:137], v[162:163], v[36:37] op_sel_hi:[1,0,1]
	v_pk_mul_f32 v[168:169], v[168:169], v[170:171]
	v_pk_mul_f32 v[170:171], v[142:143], v[142:143]
	v_pk_mul_f32 v[168:169], v[174:175], v[168:169]
	v_pk_fma_f32 v[138:139], v[138:139], v[162:163], v[38:39] op_sel_hi:[1,0,1]
	v_pk_mul_f32 v[174:175], v[166:167], v[168:169]
	v_pk_fma_f32 v[168:169], v[166:167], v[168:169], v[166:167] neg_lo:[1,0,0] neg_hi:[1,0,0]
	v_and_b32_e32 v166, 0x7fffffff, v142
	v_cndmask_b32_e32 v157, v168, v174, vcc
	v_cmp_gt_f32_e32 vcc, 0, v167
	v_and_b32_e32 v167, 0x7fffffff, v143
	v_pk_fma_f32 v[166:167], v[166:167], s[82:83], 1.0 op_sel_hi:[1,0,0]
	v_cndmask_b32_e32 v174, v169, v175, vcc
	v_rcp_f32_e32 v166, v166
	v_rcp_f32_e32 v167, v167
	v_cmp_gt_f32_e32 vcc, 0, v142
	v_lshl_add_u64 v[160:161], s[12:13], 0, v[160:161]
	v_lshl_add_u64 v[160:161], v[154:155], 1, v[160:161]
	v_pk_fma_f32 v[168:169], v[166:167], s[84:85], v[140:141] op_sel_hi:[1,0,0]
	v_pk_fma_f32 v[132:133], v[132:133], v[162:163], v[28:29] op_sel_hi:[1,0,1]
	v_pk_fma_f32 v[168:169], v[166:167], v[168:169], s[88:89] op_sel_hi:[1,1,0]
	v_pk_fma_f32 v[134:135], v[134:135], v[162:163], v[30:31] op_sel_hi:[1,0,1]
	v_pk_fma_f32 v[168:169], v[166:167], v[168:169], s[90:91] op_sel_hi:[1,1,0]
	v_pk_fma_f32 v[128:129], v[128:129], v[162:163], v[24:25] op_sel_hi:[1,0,1]
	v_pk_fma_f32 v[168:169], v[166:167], v[168:169], s[92:93] op_sel_hi:[1,1,0]
	v_pk_fma_f32 v[130:131], v[130:131], v[162:163], v[26:27] op_sel_hi:[1,0,1]
	v_pk_mul_f32 v[166:167], v[166:167], v[168:169]
	v_pk_mul_f32 v[168:169], v[170:171], s[94:95] op_sel_hi:[1,0]
	s_nop 0
	v_exp_f32_e32 v168, v168
	v_exp_f32_e32 v169, v169
	s_nop 0
	v_pk_mul_f32 v[166:167], v[168:169], v[166:167]
	s_nop 0
	v_pk_mul_f32 v[168:169], v[142:143], v[166:167]
	v_pk_fma_f32 v[166:167], v[142:143], v[166:167], v[142:143] neg_lo:[1,0,0] neg_hi:[1,0,0]
	v_and_b32_e32 v142, 0x7fffffff, v136
	v_cndmask_b32_e32 v170, v166, v168, vcc
	v_cmp_gt_f32_e32 vcc, 0, v143
	v_and_b32_e32 v143, 0x7fffffff, v137
	v_pk_fma_f32 v[142:143], v[142:143], s[82:83], 1.0 op_sel_hi:[1,0,0]
	v_cndmask_b32_e32 v171, v167, v169, vcc
	v_rcp_f32_e32 v142, v142
	v_rcp_f32_e32 v143, v143
	v_pk_mul_f32 v[168:169], v[136:137], v[136:137]
	v_cmp_gt_f32_e32 vcc, 0, v136
	v_pk_mul_f32 v[168:169], v[168:169], s[94:95] op_sel_hi:[1,0]
	v_pk_fma_f32 v[166:167], v[142:143], s[84:85], v[140:141] op_sel_hi:[1,0,0]
	v_exp_f32_e32 v168, v168
	v_pk_fma_f32 v[166:167], v[142:143], v[166:167], s[88:89] op_sel_hi:[1,1,0]
	v_exp_f32_e32 v169, v169
	v_pk_fma_f32 v[166:167], v[142:143], v[166:167], s[90:91] op_sel_hi:[1,1,0]
	s_nop 0
	v_pk_fma_f32 v[166:167], v[142:143], v[166:167], s[92:93] op_sel_hi:[1,1,0]
	s_nop 0
	v_pk_mul_f32 v[142:143], v[142:143], v[166:167]
	v_pk_mul_f32 v[166:167], v[138:139], v[138:139]
	v_pk_mul_f32 v[142:143], v[168:169], v[142:143]
	s_nop 0
	v_pk_mul_f32 v[168:169], v[136:137], v[142:143]
	v_pk_fma_f32 v[142:143], v[136:137], v[142:143], v[136:137] neg_lo:[1,0,0] neg_hi:[1,0,0]
	v_and_b32_e32 v136, 0x7fffffff, v138
	v_cndmask_b32_e32 v168, v142, v168, vcc
	v_cmp_gt_f32_e32 vcc, 0, v137
	v_and_b32_e32 v137, 0x7fffffff, v139
	v_pk_fma_f32 v[136:137], v[136:137], s[82:83], 1.0 op_sel_hi:[1,0,0]
	v_cndmask_b32_e32 v169, v143, v169, vcc
	v_rcp_f32_e32 v136, v136
	v_rcp_f32_e32 v137, v137
	v_cmp_gt_f32_e32 vcc, 0, v138
	v_pk_fma_f32 v[142:143], v[136:137], s[84:85], v[140:141] op_sel_hi:[1,0,0]
	s_nop 0
	v_pk_fma_f32 v[142:143], v[136:137], v[142:143], s[88:89] op_sel_hi:[1,1,0]
	s_nop 0
	v_pk_fma_f32 v[142:143], v[136:137], v[142:143], s[90:91] op_sel_hi:[1,1,0]
	s_nop 0
	v_pk_fma_f32 v[142:143], v[136:137], v[142:143], s[92:93] op_sel_hi:[1,1,0]
	s_nop 0
	v_pk_mul_f32 v[136:137], v[136:137], v[142:143]
	v_pk_mul_f32 v[142:143], v[166:167], s[94:95] op_sel_hi:[1,0]
	s_nop 0
	v_exp_f32_e32 v142, v142
	v_exp_f32_e32 v143, v143
; __device__ __forceinline__ unsigned cvt_pk_bf16(float lo, float hi) { unsigned r; asm volatile("v_cvt_pk_bf16_f32 %0, %1, %2" : "=v"(r) : "v"(lo), "v"(hi)); return r; }
; __device__ __forceinline__ f32x2 gelu_pk(f32x2 v) {
;     const f32x2 av = __builtin_elementwise_abs(v), d = av * 0.2316418882f + 1.0f;
;     f32x2 t; t.x = __builtin_amdgcn_rcpf(d.x); t.y = __builtin_amdgcn_rcpf(d.y);
;     f32x2 q = t * 0.5307027145f + (-0.7265760135f); q = q * t + 0.7107068705f; q = q * t + (-0.142248368f); q = q * t + 0.127414796f; q = q * t;
;     const f32x2 s = (v * v) * (-0.72134752044f);
;     f32x2 e; e.x = __builtin_amdgcn_exp2f(s.x); e.y = __builtin_amdgcn_exp2f(s.y);
;     const f32x2 m = v * (q * e), r = v - m;
;     f32x2 o; o.x = v.x < 0.f ? m.x : r.x; o.y = v.y < 0.f ? m.y : r.y; return o;
; }
;     __device__ __forceinline__ void operator()(const f32x4 (&acc)[2][2][4][2], const Unit& u, int wr, int wc, int fr, int fq) const {
;     ...
;             for (int m = 0; m < 4; ++m) { bf16_t* rowp = O + (size_t)(row0 + ai * HALF + m * 16) * ldc + col0;
;                 const float rr = fused ? __builtin_amdgcn_rsqf(ssq[row0 + ai * HALF + m * 16] * inv_n + EPS) : 1.f;
; #pragma unroll
;                 for (int bj = 0; bj < 2; ++bj) { const f32x4 v0 = act4(acc[ai][bj][m][0] * rr + bv[bj][0], ACT), v1 = act4(acc[ai][bj][m][1] * rr + bv[bj][1], ACT);
;                     u32x4 w; w.x = cvt_pk_bf16(v0[0], v0[1]); w.y = cvt_pk_bf16(v0[2], v0[3]); w.z = cvt_pk_bf16(v1[0], v1[1]); w.w = cvt_pk_bf16(v1[2], v1[3]);
;                     *(u32x4*)(rowp + bj * 32) = w; } }
	s_nop 0
	v_pk_mul_f32 v[136:137], v[142:143], v[136:137]
	s_nop 0
	v_pk_mul_f32 v[142:143], v[138:139], v[136:137]
	v_pk_fma_f32 v[136:137], v[138:139], v[136:137], v[138:139] neg_lo:[1,0,0] neg_hi:[1,0,0]
	s_nop 0
	v_cndmask_b32_e32 v142, v136, v142, vcc
	v_cmp_gt_f32_e32 vcc, 0, v139
	v_cvt_pk_bf16_f32 v136, v157, v174
	s_nop 1
	v_cndmask_b32_e32 v139, v137, v143, vcc
	v_cvt_pk_bf16_f32 v137, v170, v171
	v_cvt_pk_bf16_f32 v138, v168, v169
	v_cvt_pk_bf16_f32 v139, v142, v139
	global_store_dwordx4 v[160:161], v[136:139], off
	v_pk_mul_f32 v[142:143], v[132:133], v[132:133]
	v_cmp_gt_f32_e32 vcc, 0, v132
	v_and_b32_e32 v137, 0x7fffffff, v133
	v_and_b32_e32 v136, 0x7fffffff, v132
	v_pk_fma_f32 v[136:137], v[136:137], s[82:83], 1.0 op_sel_hi:[1,0,0]
	v_pk_mul_f32 v[142:143], v[142:143], s[94:95] op_sel_hi:[1,0]
	v_rcp_f32_e32 v136, v136
	v_rcp_f32_e32 v137, v137
	v_exp_f32_e32 v142, v142
	v_exp_f32_e32 v143, v143
	v_pk_fma_f32 v[138:139], v[136:137], s[84:85], v[140:141] op_sel_hi:[1,0,0]
	s_nop 0
	v_pk_fma_f32 v[138:139], v[136:137], v[138:139], s[88:89] op_sel_hi:[1,1,0]
	s_nop 0
	v_pk_fma_f32 v[138:139], v[136:137], v[138:139], s[90:91] op_sel_hi:[1,1,0]
	s_nop 0
	v_pk_fma_f32 v[138:139], v[136:137], v[138:139], s[92:93] op_sel_hi:[1,1,0]
	s_nop 0
	v_pk_mul_f32 v[136:137], v[136:137], v[138:139]
	v_pk_mul_f32 v[138:139], v[134:135], v[134:135]
	v_pk_mul_f32 v[136:137], v[142:143], v[136:137]
	s_nop 0
	v_pk_mul_f32 v[142:143], v[132:133], v[136:137]
	v_pk_fma_f32 v[136:137], v[132:133], v[136:137], v[132:133] neg_lo:[1,0,0] neg_hi:[1,0,0]
	v_and_b32_e32 v132, 0x7fffffff, v134
	v_cndmask_b32_e32 v142, v136, v142, vcc
	v_cmp_gt_f32_e32 vcc, 0, v133
	v_and_b32_e32 v133, 0x7fffffff, v135
	v_pk_fma_f32 v[132:133], v[132:133], s[82:83], 1.0 op_sel_hi:[1,0,0]
	v_cndmask_b32_e32 v143, v137, v143, vcc
	v_rcp_f32_e32 v132, v132
	v_rcp_f32_e32 v133, v133
	v_cmp_gt_f32_e32 vcc, 0, v134
	v_pk_fma_f32 v[136:137], v[132:133], s[84:85], v[140:141] op_sel_hi:[1,0,0]
	s_nop 0
	v_pk_fma_f32 v[136:137], v[132:133], v[136:137], s[88:89] op_sel_hi:[1,1,0]
	s_nop 0
	v_pk_fma_f32 v[136:137], v[132:133], v[136:137], s[90:91] op_sel_hi:[1,1,0]
	s_nop 0
	v_pk_fma_f32 v[136:137], v[132:133], v[136:137], s[92:93] op_sel_hi:[1,1,0]
	s_nop 0
	v_pk_mul_f32 v[132:133], v[132:133], v[136:137]
	v_pk_mul_f32 v[136:137], v[138:139], s[94:95] op_sel_hi:[1,0]
	s_nop 0
	v_exp_f32_e32 v136, v136
	v_exp_f32_e32 v137, v137
	s_nop 0
	v_pk_mul_f32 v[132:133], v[136:137], v[132:133]
	s_nop 0
	v_pk_mul_f32 v[136:137], v[134:135], v[132:133]
	v_pk_fma_f32 v[132:133], v[134:135], v[132:133], v[134:135] neg_lo:[1,0,0] neg_hi:[1,0,0]
	s_nop 0
	v_cndmask_b32_e32 v138, v132, v136, vcc
	v_cmp_gt_f32_e32 vcc, 0, v135
	v_and_b32_e32 v132, 0x7fffffff, v128
	s_nop 0
	v_cndmask_b32_e32 v139, v133, v137, vcc
	v_and_b32_e32 v133, 0x7fffffff, v129
	v_pk_fma_f32 v[132:133], v[132:133], s[82:83], 1.0 op_sel_hi:[1,0,0]
	v_pk_mul_f32 v[136:137], v[128:129], v[128:129]
	v_rcp_f32_e32 v132, v132
	v_rcp_f32_e32 v133, v133
	v_pk_mul_f32 v[136:137], v[136:137], s[94:95] op_sel_hi:[1,0]
	v_cmp_gt_f32_e32 vcc, 0, v128
	v_exp_f32_e32 v136, v136
	v_pk_fma_f32 v[134:135], v[132:133], s[84:85], v[140:141] op_sel_hi:[1,0,0]
	v_exp_f32_e32 v137, v137
	v_pk_fma_f32 v[134:135], v[132:133], v[134:135], s[88:89] op_sel_hi:[1,1,0]
	s_nop 0
	v_pk_fma_f32 v[134:135], v[132:133], v[134:135], s[90:91] op_sel_hi:[1,1,0]
	s_nop 0
	v_pk_fma_f32 v[134:135], v[132:133], v[134:135], s[92:93] op_sel_hi:[1,1,0]
	s_nop 0
	v_pk_mul_f32 v[132:133], v[132:133], v[134:135]
	v_pk_mul_f32 v[134:135], v[130:131], v[130:131]
	v_pk_mul_f32 v[132:133], v[136:137], v[132:133]
	s_nop 0
	v_pk_mul_f32 v[136:137], v[128:129], v[132:133]
	v_pk_fma_f32 v[132:133], v[128:129], v[132:133], v[128:129] neg_lo:[1,0,0] neg_hi:[1,0,0]
	v_and_b32_e32 v128, 0x7fffffff, v130
	v_cndmask_b32_e32 v136, v132, v136, vcc
	v_cmp_gt_f32_e32 vcc, 0, v129
	v_and_b32_e32 v129, 0x7fffffff, v131
	v_pk_fma_f32 v[128:129], v[128:129], s[82:83], 1.0 op_sel_hi:[1,0,0]
	v_cndmask_b32_e32 v137, v133, v137, vcc
	v_rcp_f32_e32 v128, v128
	v_rcp_f32_e32 v129, v129
	v_cmp_gt_f32_e32 vcc, 0, v130
	v_pk_fma_f32 v[132:133], v[128:129], s[84:85], v[140:141] op_sel_hi:[1,0,0]
	s_nop 0
	v_pk_fma_f32 v[132:133], v[128:129], v[132:133], s[88:89] op_sel_hi:[1,1,0]
	s_nop 0
	v_pk_fma_f32 v[132:133], v[128:129], v[132:133], s[90:91] op_sel_hi:[1,1,0]
	s_nop 0
	v_pk_fma_f32 v[132:133], v[128:129], v[132:133], s[92:93] op_sel_hi:[1,1,0]
	s_nop 0
	v_pk_mul_f32 v[128:129], v[128:129], v[132:133]
	v_pk_mul_f32 v[132:133], v[134:135], s[94:95] op_sel_hi:[1,0]
	s_nop 0
	v_exp_f32_e32 v132, v132
	v_exp_f32_e32 v133, v133
	s_nop 0
	v_pk_mul_f32 v[128:129], v[132:133], v[128:129]
	s_nop 0
	v_pk_mul_f32 v[132:133], v[130:131], v[128:129]
	v_pk_fma_f32 v[128:129], v[130:131], v[128:129], v[130:131] neg_lo:[1,0,0] neg_hi:[1,0,0]
	s_nop 0
	v_cndmask_b32_e32 v132, v128, v132, vcc
	v_cmp_gt_f32_e32 vcc, 0, v131
	v_cvt_pk_bf16_f32 v128, v142, v143
	s_nop 1
	v_cndmask_b32_e32 v131, v129, v133, vcc
	v_cvt_pk_bf16_f32 v129, v138, v139
	v_cvt_pk_bf16_f32 v130, v136, v137
	v_cvt_pk_bf16_f32 v131, v132, v131
	global_store_dwordx4 v[160:161], v[128:131], off offset:64
	s_and_b64 vcc, exec, s[8:9]
	s_nop 0
	v_or_b32_e32 v128, 16, v156
	v_ashrrev_i32_e32 v129, 31, v128
	s_cbranch_vccnz .LBB0_290
	v_lshl_add_u64 v[130:131], v[128:129], 2, s[54:55]
	s_nop 2
	v_mov_b32_e32 v130, v251
	v_fmamk_f32 v130, v130, 0x3a800000, v189
	v_rsq_f32_e32 v158, v130
; __device__ __forceinline__ unsigned cvt_pk_bf16(float lo, float hi) { unsigned r; asm volatile("v_cvt_pk_bf16_f32 %0, %1, %2" : "=v"(r) : "v"(lo), "v"(hi)); return r; }
; __device__ __forceinline__ f32x2 gelu_pk(f32x2 v) {
;     const f32x2 av = __builtin_elementwise_abs(v), d = av * 0.2316418882f + 1.0f;
;     f32x2 t; t.x = __builtin_amdgcn_rcpf(d.x); t.y = __builtin_amdgcn_rcpf(d.y);
;     f32x2 q = t * 0.5307027145f + (-0.7265760135f); q = q * t + 0.7107068705f; q = q * t + (-0.142248368f); q = q * t + 0.127414796f; q = q * t;
;     const f32x2 s = (v * v) * (-0.72134752044f);
;     f32x2 e; e.x = __builtin_amdgcn_exp2f(s.x); e.y = __builtin_amdgcn_exp2f(s.y);
;     const f32x2 m = v * (q * e), r = v - m;
;     f32x2 o; o.x = v.x < 0.f ? m.x : r.x; o.y = v.y < 0.f ? m.y : r.y; return o;
; }
;     __device__ __forceinline__ void operator()(const f32x4 (&acc)[2][2][4][2], const Unit& u, int wr, int wc, int fr, int fq) const {
;     ...
;             for (int m = 0; m < 4; ++m) { bf16_t* rowp = O + (size_t)(row0 + ai * HALF + m * 16) * ldc + col0;
;                 const float rr = fused ? __builtin_amdgcn_rsqf(ssq[row0 + ai * HALF + m * 16] * inv_n + EPS) : 1.f;
; #pragma unroll
;                 for (int bj = 0; bj < 2; ++bj) { const f32x4 v0 = act4(acc[ai][bj][m][0] * rr + bv[bj][0], ACT), v1 = act4(acc[ai][bj][m][1] * rr + bv[bj][1], ACT);
;                     u32x4 w; w.x = cvt_pk_bf16(v0[0], v0[1]); w.y = cvt_pk_bf16(v0[2], v0[3]); w.z = cvt_pk_bf16(v1[0], v1[1]); w.w = cvt_pk_bf16(v1[2], v1[3]);
;                     *(u32x4*)(rowp + bj * 32) = w; } }
.LBB0_290:
	s_nop 0
	v_pk_fma_f32 v[130:131], v[124:125], v[158:159], v[44:45] op_sel_hi:[1,0,1]
	v_pk_fma_f32 v[126:127], v[126:127], v[158:159], v[46:47] op_sel_hi:[1,0,1]
	v_and_b32_e32 v125, 0x7fffffff, v131
	v_and_b32_e32 v124, 0x7fffffff, v130
	v_pk_fma_f32 v[124:125], v[124:125], s[82:83], 1.0 op_sel_hi:[1,0,0]
	v_pk_mul_f32 v[136:137], v[130:131], v[130:131]
	v_rcp_f32_e32 v132, v124
	v_rcp_f32_e32 v133, v125
	v_mov_b64_e32 v[124:125], s[70:71]
	v_pk_mul_f32 v[136:137], v[136:137], s[94:95] op_sel_hi:[1,0]
	v_cmp_gt_f32_e32 vcc, 0, v130
	v_pk_fma_f32 v[134:135], v[132:133], s[84:85], v[124:125] op_sel_hi:[1,0,0]
	v_exp_f32_e32 v136, v136
	v_pk_fma_f32 v[134:135], v[132:133], v[134:135], s[88:89] op_sel_hi:[1,1,0]
	v_exp_f32_e32 v137, v137
	v_pk_fma_f32 v[134:135], v[132:133], v[134:135], s[90:91] op_sel_hi:[1,1,0]
	v_pk_fma_f32 v[120:121], v[120:121], v[158:159], v[36:37] op_sel_hi:[1,0,1]
	v_pk_fma_f32 v[134:135], v[132:133], v[134:135], s[92:93] op_sel_hi:[1,1,0]
	v_pk_fma_f32 v[122:123], v[122:123], v[158:159], v[38:39] op_sel_hi:[1,0,1]
	v_pk_mul_f32 v[132:133], v[132:133], v[134:135]
	v_pk_mul_f32 v[134:135], v[126:127], v[126:127]
	v_pk_mul_f32 v[132:133], v[136:137], v[132:133]
	v_lshlrev_b64 v[128:129], 12, v[128:129]
	v_pk_mul_f32 v[136:137], v[130:131], v[132:133]
	v_pk_fma_f32 v[132:133], v[130:131], v[132:133], v[130:131] neg_lo:[1,0,0] neg_hi:[1,0,0]
	v_and_b32_e32 v130, 0x7fffffff, v126
	v_cndmask_b32_e32 v136, v132, v136, vcc
	v_cmp_gt_f32_e32 vcc, 0, v131
	v_and_b32_e32 v131, 0x7fffffff, v127
	v_pk_fma_f32 v[130:131], v[130:131], s[82:83], 1.0 op_sel_hi:[1,0,0]
	v_cndmask_b32_e32 v137, v133, v137, vcc
	v_rcp_f32_e32 v130, v130
	v_rcp_f32_e32 v131, v131
	v_cmp_gt_f32_e32 vcc, 0, v126
	v_lshl_add_u64 v[128:129], s[12:13], 0, v[128:129]
	v_lshl_add_u64 v[128:129], v[154:155], 1, v[128:129]
	v_pk_fma_f32 v[132:133], v[130:131], s[84:85], v[124:125] op_sel_hi:[1,0,0]
	v_pk_fma_f32 v[116:117], v[116:117], v[158:159], v[28:29] op_sel_hi:[1,0,1]
	v_pk_fma_f32 v[132:133], v[130:131], v[132:133], s[88:89] op_sel_hi:[1,1,0]
	v_pk_fma_f32 v[118:119], v[118:119], v[158:159], v[30:31] op_sel_hi:[1,0,1]
	v_pk_fma_f32 v[132:133], v[130:131], v[132:133], s[90:91] op_sel_hi:[1,1,0]
	v_pk_fma_f32 v[112:113], v[112:113], v[158:159], v[24:25] op_sel_hi:[1,0,1]
	v_pk_fma_f32 v[132:133], v[130:131], v[132:133], s[92:93] op_sel_hi:[1,1,0]
	v_pk_fma_f32 v[114:115], v[114:115], v[158:159], v[26:27] op_sel_hi:[1,0,1]
	v_pk_mul_f32 v[130:131], v[130:131], v[132:133]
	v_pk_mul_f32 v[132:133], v[134:135], s[94:95] op_sel_hi:[1,0]
	s_nop 0
	v_exp_f32_e32 v132, v132
	v_exp_f32_e32 v133, v133
	s_nop 0
	v_pk_mul_f32 v[130:131], v[132:133], v[130:131]
	s_nop 0
	v_pk_mul_f32 v[132:133], v[126:127], v[130:131]
	v_pk_fma_f32 v[130:131], v[126:127], v[130:131], v[126:127] neg_lo:[1,0,0] neg_hi:[1,0,0]
	v_and_b32_e32 v126, 0x7fffffff, v120
	v_cndmask_b32_e32 v134, v130, v132, vcc
	v_cmp_gt_f32_e32 vcc, 0, v127
	v_and_b32_e32 v127, 0x7fffffff, v121
	v_pk_fma_f32 v[126:127], v[126:127], s[82:83], 1.0 op_sel_hi:[1,0,0]
	v_cndmask_b32_e32 v135, v131, v133, vcc
	v_rcp_f32_e32 v126, v126
	v_rcp_f32_e32 v127, v127
	v_pk_mul_f32 v[132:133], v[120:121], v[120:121]
	v_cmp_gt_f32_e32 vcc, 0, v120
	v_pk_mul_f32 v[132:133], v[132:133], s[94:95] op_sel_hi:[1,0]
	v_pk_fma_f32 v[130:131], v[126:127], s[84:85], v[124:125] op_sel_hi:[1,0,0]
	v_exp_f32_e32 v132, v132
	v_pk_fma_f32 v[130:131], v[126:127], v[130:131], s[88:89] op_sel_hi:[1,1,0]
	v_exp_f32_e32 v133, v133
	v_pk_fma_f32 v[130:131], v[126:127], v[130:131], s[90:91] op_sel_hi:[1,1,0]
	s_nop 0
	v_pk_fma_f32 v[130:131], v[126:127], v[130:131], s[92:93] op_sel_hi:[1,1,0]
	s_nop 0
	v_pk_mul_f32 v[126:127], v[126:127], v[130:131]
	v_pk_mul_f32 v[130:131], v[122:123], v[122:123]
	v_pk_mul_f32 v[126:127], v[132:133], v[126:127]
	s_nop 0
	v_pk_mul_f32 v[132:133], v[120:121], v[126:127]
	v_pk_fma_f32 v[126:127], v[120:121], v[126:127], v[120:121] neg_lo:[1,0,0] neg_hi:[1,0,0]
	v_and_b32_e32 v120, 0x7fffffff, v122
	v_cndmask_b32_e32 v132, v126, v132, vcc
	v_cmp_gt_f32_e32 vcc, 0, v121
	v_and_b32_e32 v121, 0x7fffffff, v123
	v_pk_fma_f32 v[120:121], v[120:121], s[82:83], 1.0 op_sel_hi:[1,0,0]
	v_cndmask_b32_e32 v133, v127, v133, vcc
	v_rcp_f32_e32 v120, v120
	v_rcp_f32_e32 v121, v121
	v_cmp_gt_f32_e32 vcc, 0, v122
	v_pk_fma_f32 v[126:127], v[120:121], s[84:85], v[124:125] op_sel_hi:[1,0,0]
	s_nop 0
	v_pk_fma_f32 v[126:127], v[120:121], v[126:127], s[88:89] op_sel_hi:[1,1,0]
	s_nop 0
	v_pk_fma_f32 v[126:127], v[120:121], v[126:127], s[90:91] op_sel_hi:[1,1,0]
	s_nop 0
	v_pk_fma_f32 v[126:127], v[120:121], v[126:127], s[92:93] op_sel_hi:[1,1,0]
	s_nop 0
	v_pk_mul_f32 v[120:121], v[120:121], v[126:127]
	v_pk_mul_f32 v[126:127], v[130:131], s[94:95] op_sel_hi:[1,0]
	s_nop 0
	v_exp_f32_e32 v126, v126
	v_exp_f32_e32 v127, v127
	s_nop 0
	v_pk_mul_f32 v[120:121], v[126:127], v[120:121]
	s_nop 0
	v_pk_mul_f32 v[126:127], v[122:123], v[120:121]
	v_pk_fma_f32 v[120:121], v[122:123], v[120:121], v[122:123] neg_lo:[1,0,0] neg_hi:[1,0,0]
	s_nop 0
	v_cndmask_b32_e32 v126, v120, v126, vcc
	v_cmp_gt_f32_e32 vcc, 0, v123
	v_cvt_pk_bf16_f32 v120, v136, v137
	s_nop 1
	v_cndmask_b32_e32 v123, v121, v127, vcc
	v_cvt_pk_bf16_f32 v121, v134, v135
	v_cvt_pk_bf16_f32 v122, v132, v133
	v_cvt_pk_bf16_f32 v123, v126, v123
	global_store_dwordx4 v[128:129], v[120:123], off
	v_pk_mul_f32 v[126:127], v[116:117], v[116:117]
	v_cmp_gt_f32_e32 vcc, 0, v116
	v_and_b32_e32 v121, 0x7fffffff, v117
	v_and_b32_e32 v120, 0x7fffffff, v116
	v_pk_fma_f32 v[120:121], v[120:121], s[82:83], 1.0 op_sel_hi:[1,0,0]
	v_pk_mul_f32 v[126:127], v[126:127], s[94:95] op_sel_hi:[1,0]
; __device__ __forceinline__ unsigned cvt_pk_bf16(float lo, float hi) { unsigned r; asm volatile("v_cvt_pk_bf16_f32 %0, %1, %2" : "=v"(r) : "v"(lo), "v"(hi)); return r; }
; __device__ __forceinline__ f32x2 gelu_pk(f32x2 v) {
;     const f32x2 av = __builtin_elementwise_abs(v), d = av * 0.2316418882f + 1.0f;
;     f32x2 t; t.x = __builtin_amdgcn_rcpf(d.x); t.y = __builtin_amdgcn_rcpf(d.y);
;     f32x2 q = t * 0.5307027145f + (-0.7265760135f); q = q * t + 0.7107068705f; q = q * t + (-0.142248368f); q = q * t + 0.127414796f; q = q * t;
;     const f32x2 s = (v * v) * (-0.72134752044f);
;     f32x2 e; e.x = __builtin_amdgcn_exp2f(s.x); e.y = __builtin_amdgcn_exp2f(s.y);
;     const f32x2 m = v * (q * e), r = v - m;
;     f32x2 o; o.x = v.x < 0.f ? m.x : r.x; o.y = v.y < 0.f ? m.y : r.y; return o;
; }
;     __device__ __forceinline__ void operator()(const f32x4 (&acc)[2][2][4][2], const Unit& u, int wr, int wc, int fr, int fq) const {
;     ...
;             for (int m = 0; m < 4; ++m) { bf16_t* rowp = O + (size_t)(row0 + ai * HALF + m * 16) * ldc + col0;
;                 const float rr = fused ? __builtin_amdgcn_rsqf(ssq[row0 + ai * HALF + m * 16] * inv_n + EPS) : 1.f;
; #pragma unroll
;                 for (int bj = 0; bj < 2; ++bj) { const f32x4 v0 = act4(acc[ai][bj][m][0] * rr + bv[bj][0], ACT), v1 = act4(acc[ai][bj][m][1] * rr + bv[bj][1], ACT);
;                     u32x4 w; w.x = cvt_pk_bf16(v0[0], v0[1]); w.y = cvt_pk_bf16(v0[2], v0[3]); w.z = cvt_pk_bf16(v1[0], v1[1]); w.w = cvt_pk_bf16(v1[2], v1[3]);
;                     *(u32x4*)(rowp + bj * 32) = w; } }
	v_rcp_f32_e32 v120, v120
	v_rcp_f32_e32 v121, v121
	v_exp_f32_e32 v126, v126
	v_exp_f32_e32 v127, v127
	v_pk_fma_f32 v[122:123], v[120:121], s[84:85], v[124:125] op_sel_hi:[1,0,0]
	s_nop 0
	v_pk_fma_f32 v[122:123], v[120:121], v[122:123], s[88:89] op_sel_hi:[1,1,0]
	s_nop 0
	v_pk_fma_f32 v[122:123], v[120:121], v[122:123], s[90:91] op_sel_hi:[1,1,0]
	s_nop 0
	v_pk_fma_f32 v[122:123], v[120:121], v[122:123], s[92:93] op_sel_hi:[1,1,0]
	s_nop 0
	v_pk_mul_f32 v[120:121], v[120:121], v[122:123]
	v_pk_mul_f32 v[122:123], v[118:119], v[118:119]
	v_pk_mul_f32 v[120:121], v[126:127], v[120:121]
	s_nop 0
	v_pk_mul_f32 v[126:127], v[116:117], v[120:121]
	v_pk_fma_f32 v[120:121], v[116:117], v[120:121], v[116:117] neg_lo:[1,0,0] neg_hi:[1,0,0]
	v_and_b32_e32 v116, 0x7fffffff, v118
	v_cndmask_b32_e32 v126, v120, v126, vcc
	v_cmp_gt_f32_e32 vcc, 0, v117
	v_and_b32_e32 v117, 0x7fffffff, v119
	v_pk_fma_f32 v[116:117], v[116:117], s[82:83], 1.0 op_sel_hi:[1,0,0]
	v_cndmask_b32_e32 v127, v121, v127, vcc
	v_rcp_f32_e32 v116, v116
	v_rcp_f32_e32 v117, v117
	v_cmp_gt_f32_e32 vcc, 0, v118
	v_pk_fma_f32 v[120:121], v[116:117], s[84:85], v[124:125] op_sel_hi:[1,0,0]
	s_nop 0
	v_pk_fma_f32 v[120:121], v[116:117], v[120:121], s[88:89] op_sel_hi:[1,1,0]
	s_nop 0
	v_pk_fma_f32 v[120:121], v[116:117], v[120:121], s[90:91] op_sel_hi:[1,1,0]
	s_nop 0
	v_pk_fma_f32 v[120:121], v[116:117], v[120:121], s[92:93] op_sel_hi:[1,1,0]
	s_nop 0
	v_pk_mul_f32 v[116:117], v[116:117], v[120:121]
	v_pk_mul_f32 v[120:121], v[122:123], s[94:95] op_sel_hi:[1,0]
	s_nop 0
	v_exp_f32_e32 v120, v120
	v_exp_f32_e32 v121, v121
	s_nop 0
	v_pk_mul_f32 v[116:117], v[120:121], v[116:117]
	s_nop 0
	v_pk_mul_f32 v[120:121], v[118:119], v[116:117]
	v_pk_fma_f32 v[116:117], v[118:119], v[116:117], v[118:119] neg_lo:[1,0,0] neg_hi:[1,0,0]
	s_nop 0
	v_cndmask_b32_e32 v122, v116, v120, vcc
	v_cmp_gt_f32_e32 vcc, 0, v119
	v_and_b32_e32 v116, 0x7fffffff, v112
	s_nop 0
	v_cndmask_b32_e32 v123, v117, v121, vcc
	v_and_b32_e32 v117, 0x7fffffff, v113
	v_pk_fma_f32 v[116:117], v[116:117], s[82:83], 1.0 op_sel_hi:[1,0,0]
	v_pk_mul_f32 v[120:121], v[112:113], v[112:113]
	v_rcp_f32_e32 v116, v116
	v_rcp_f32_e32 v117, v117
	v_pk_mul_f32 v[120:121], v[120:121], s[94:95] op_sel_hi:[1,0]
	v_cmp_gt_f32_e32 vcc, 0, v112
	v_exp_f32_e32 v120, v120
	v_pk_fma_f32 v[118:119], v[116:117], s[84:85], v[124:125] op_sel_hi:[1,0,0]
	v_exp_f32_e32 v121, v121
	v_pk_fma_f32 v[118:119], v[116:117], v[118:119], s[88:89] op_sel_hi:[1,1,0]
	s_nop 0
	v_pk_fma_f32 v[118:119], v[116:117], v[118:119], s[90:91] op_sel_hi:[1,1,0]
	s_nop 0
	v_pk_fma_f32 v[118:119], v[116:117], v[118:119], s[92:93] op_sel_hi:[1,1,0]
	s_nop 0
	v_pk_mul_f32 v[116:117], v[116:117], v[118:119]
	v_pk_mul_f32 v[118:119], v[114:115], v[114:115]
	v_pk_mul_f32 v[116:117], v[120:121], v[116:117]
	s_nop 0
	v_pk_mul_f32 v[120:121], v[112:113], v[116:117]
	v_pk_fma_f32 v[116:117], v[112:113], v[116:117], v[112:113] neg_lo:[1,0,0] neg_hi:[1,0,0]
	v_and_b32_e32 v112, 0x7fffffff, v114
	v_cndmask_b32_e32 v120, v116, v120, vcc
	v_cmp_gt_f32_e32 vcc, 0, v113
	v_and_b32_e32 v113, 0x7fffffff, v115
	v_pk_fma_f32 v[112:113], v[112:113], s[82:83], 1.0 op_sel_hi:[1,0,0]
	v_cndmask_b32_e32 v121, v117, v121, vcc
	v_rcp_f32_e32 v112, v112
	v_rcp_f32_e32 v113, v113
	v_cmp_gt_f32_e32 vcc, 0, v114
	v_pk_fma_f32 v[116:117], v[112:113], s[84:85], v[124:125] op_sel_hi:[1,0,0]
	s_nop 0
	v_pk_fma_f32 v[116:117], v[112:113], v[116:117], s[88:89] op_sel_hi:[1,1,0]
	s_nop 0
	v_pk_fma_f32 v[116:117], v[112:113], v[116:117], s[90:91] op_sel_hi:[1,1,0]
	s_nop 0
	v_pk_fma_f32 v[116:117], v[112:113], v[116:117], s[92:93] op_sel_hi:[1,1,0]
	s_nop 0
	v_pk_mul_f32 v[112:113], v[112:113], v[116:117]
	v_pk_mul_f32 v[116:117], v[118:119], s[94:95] op_sel_hi:[1,0]
	s_nop 0
	v_exp_f32_e32 v116, v116
	v_exp_f32_e32 v117, v117
	s_nop 0
	v_pk_mul_f32 v[112:113], v[116:117], v[112:113]
	s_nop 0
	v_pk_mul_f32 v[116:117], v[114:115], v[112:113]
	v_pk_fma_f32 v[112:113], v[114:115], v[112:113], v[114:115] neg_lo:[1,0,0] neg_hi:[1,0,0]
	s_nop 0
	v_cndmask_b32_e32 v116, v112, v116, vcc
	v_cmp_gt_f32_e32 vcc, 0, v115
	v_cvt_pk_bf16_f32 v112, v126, v127
	s_nop 1
	v_cndmask_b32_e32 v115, v113, v117, vcc
	v_cvt_pk_bf16_f32 v113, v122, v123
	v_cvt_pk_bf16_f32 v114, v120, v121
	v_cvt_pk_bf16_f32 v115, v116, v115
	global_store_dwordx4 v[128:129], v[112:115], off offset:64
	s_and_b64 vcc, exec, s[8:9]
	v_mov_b32_e32 v116, 1.0
	v_or_b32_e32 v114, 32, v156
	v_ashrrev_i32_e32 v115, 31, v114
	v_mov_b32_e32 v112, 1.0
	s_cbranch_vccnz .LBB0_292
	v_lshl_add_u64 v[116:117], v[114:115], 2, s[54:55]
	s_nop 2
	v_mov_b32_e32 v113, v250
	v_fmamk_f32 v113, v113, 0x3a800000, v189
	v_rsq_f32_e32 v116, v113
; __device__ __forceinline__ unsigned cvt_pk_bf16(float lo, float hi) { unsigned r; asm volatile("v_cvt_pk_bf16_f32 %0, %1, %2" : "=v"(r) : "v"(lo), "v"(hi)); return r; }
; __device__ __forceinline__ f32x2 gelu_pk(f32x2 v) {
;     const f32x2 av = __builtin_elementwise_abs(v), d = av * 0.2316418882f + 1.0f;
;     f32x2 t; t.x = __builtin_amdgcn_rcpf(d.x); t.y = __builtin_amdgcn_rcpf(d.y);
;     f32x2 q = t * 0.5307027145f + (-0.7265760135f); q = q * t + 0.7107068705f; q = q * t + (-0.142248368f); q = q * t + 0.127414796f; q = q * t;
;     const f32x2 s = (v * v) * (-0.72134752044f);
;     f32x2 e; e.x = __builtin_amdgcn_exp2f(s.x); e.y = __builtin_amdgcn_exp2f(s.y);
;     const f32x2 m = v * (q * e), r = v - m;
;     f32x2 o; o.x = v.x < 0.f ? m.x : r.x; o.y = v.y < 0.f ? m.y : r.y; return o;
; }
;     __device__ __forceinline__ void operator()(const f32x4 (&acc)[2][2][4][2], const Unit& u, int wr, int wc, int fr, int fq) const {
;     ...
;             for (int m = 0; m < 4; ++m) { bf16_t* rowp = O + (size_t)(row0 + ai * HALF + m * 16) * ldc + col0;
;                 const float rr = fused ? __builtin_amdgcn_rsqf(ssq[row0 + ai * HALF + m * 16] * inv_n + EPS) : 1.f;
; #pragma unroll
;                 for (int bj = 0; bj < 2; ++bj) { const f32x4 v0 = act4(acc[ai][bj][m][0] * rr + bv[bj][0], ACT), v1 = act4(acc[ai][bj][m][1] * rr + bv[bj][1], ACT);
;                     u32x4 w; w.x = cvt_pk_bf16(v0[0], v0[1]); w.y = cvt_pk_bf16(v0[2], v0[3]); w.z = cvt_pk_bf16(v1[0], v1[1]); w.w = cvt_pk_bf16(v1[2], v1[3]);
;                     *(u32x4*)(rowp + bj * 32) = w; } }
.LBB0_292:
	s_nop 0
	v_pk_fma_f32 v[118:119], v[108:109], v[116:117], v[44:45] op_sel_hi:[1,0,1]
	v_pk_fma_f32 v[110:111], v[110:111], v[116:117], v[46:47] op_sel_hi:[1,0,1]
	v_and_b32_e32 v109, 0x7fffffff, v119
	v_and_b32_e32 v108, 0x7fffffff, v118
	v_pk_fma_f32 v[108:109], v[108:109], s[82:83], 1.0 op_sel_hi:[1,0,0]
	v_pk_mul_f32 v[124:125], v[118:119], v[118:119]
	v_rcp_f32_e32 v120, v108
	v_rcp_f32_e32 v121, v109
	v_mov_b64_e32 v[108:109], s[70:71]
	v_pk_mul_f32 v[124:125], v[124:125], s[94:95] op_sel_hi:[1,0]
	v_cmp_gt_f32_e32 vcc, 0, v118
	v_pk_fma_f32 v[122:123], v[120:121], s[84:85], v[108:109] op_sel_hi:[1,0,0]
	v_exp_f32_e32 v124, v124
	v_pk_fma_f32 v[122:123], v[120:121], v[122:123], s[88:89] op_sel_hi:[1,1,0]
	v_exp_f32_e32 v125, v125
	v_pk_fma_f32 v[122:123], v[120:121], v[122:123], s[90:91] op_sel_hi:[1,1,0]
	v_lshlrev_b64 v[114:115], 12, v[114:115]
	v_pk_fma_f32 v[122:123], v[120:121], v[122:123], s[92:93] op_sel_hi:[1,1,0]
	v_lshl_add_u64 v[114:115], s[12:13], 0, v[114:115]
	v_pk_mul_f32 v[120:121], v[120:121], v[122:123]
	v_pk_mul_f32 v[122:123], v[110:111], v[110:111]
	v_pk_mul_f32 v[120:121], v[124:125], v[120:121]
	v_lshl_add_u64 v[114:115], v[154:155], 1, v[114:115]
	v_pk_mul_f32 v[124:125], v[118:119], v[120:121]
	v_pk_fma_f32 v[120:121], v[118:119], v[120:121], v[118:119] neg_lo:[1,0,0] neg_hi:[1,0,0]
	v_and_b32_e32 v118, 0x7fffffff, v110
	v_cndmask_b32_e32 v113, v120, v124, vcc
	v_cmp_gt_f32_e32 vcc, 0, v119
	v_and_b32_e32 v119, 0x7fffffff, v111
	v_pk_fma_f32 v[118:119], v[118:119], s[82:83], 1.0 op_sel_hi:[1,0,0]
	v_cndmask_b32_e32 v117, v121, v125, vcc
	v_rcp_f32_e32 v118, v118
	v_rcp_f32_e32 v119, v119
	v_cmp_gt_f32_e32 vcc, 0, v110
	v_pk_fma_f32 v[104:105], v[104:105], v[116:117], v[36:37] op_sel_hi:[1,0,1]
	v_pk_fma_f32 v[106:107], v[106:107], v[116:117], v[38:39] op_sel_hi:[1,0,1]
	v_pk_fma_f32 v[120:121], v[118:119], s[84:85], v[108:109] op_sel_hi:[1,0,0]
	v_pk_fma_f32 v[100:101], v[100:101], v[116:117], v[28:29] op_sel_hi:[1,0,1]
	v_pk_fma_f32 v[120:121], v[118:119], v[120:121], s[88:89] op_sel_hi:[1,1,0]
	v_pk_fma_f32 v[102:103], v[102:103], v[116:117], v[30:31] op_sel_hi:[1,0,1]
	v_pk_fma_f32 v[120:121], v[118:119], v[120:121], s[90:91] op_sel_hi:[1,1,0]
	v_pk_fma_f32 v[96:97], v[96:97], v[116:117], v[24:25] op_sel_hi:[1,0,1]
	v_pk_fma_f32 v[120:121], v[118:119], v[120:121], s[92:93] op_sel_hi:[1,1,0]
	v_pk_fma_f32 v[98:99], v[98:99], v[116:117], v[26:27] op_sel_hi:[1,0,1]
	v_pk_mul_f32 v[118:119], v[118:119], v[120:121]
	v_pk_mul_f32 v[120:121], v[122:123], s[94:95] op_sel_hi:[1,0]
	s_nop 0
	v_exp_f32_e32 v120, v120
	v_exp_f32_e32 v121, v121
	s_nop 0
	v_pk_mul_f32 v[118:119], v[120:121], v[118:119]
	s_nop 0
	v_pk_mul_f32 v[120:121], v[110:111], v[118:119]
	v_pk_fma_f32 v[118:119], v[110:111], v[118:119], v[110:111] neg_lo:[1,0,0] neg_hi:[1,0,0]
	v_and_b32_e32 v110, 0x7fffffff, v104
	v_cndmask_b32_e32 v122, v118, v120, vcc
	v_cmp_gt_f32_e32 vcc, 0, v111
	v_and_b32_e32 v111, 0x7fffffff, v105
	v_pk_fma_f32 v[110:111], v[110:111], s[82:83], 1.0 op_sel_hi:[1,0,0]
	v_cndmask_b32_e32 v123, v119, v121, vcc
	v_rcp_f32_e32 v110, v110
	v_rcp_f32_e32 v111, v111
	v_pk_mul_f32 v[120:121], v[104:105], v[104:105]
	v_cmp_gt_f32_e32 vcc, 0, v104
	v_pk_mul_f32 v[120:121], v[120:121], s[94:95] op_sel_hi:[1,0]
	v_pk_fma_f32 v[118:119], v[110:111], s[84:85], v[108:109] op_sel_hi:[1,0,0]
	v_exp_f32_e32 v120, v120
	v_pk_fma_f32 v[118:119], v[110:111], v[118:119], s[88:89] op_sel_hi:[1,1,0]
	v_exp_f32_e32 v121, v121
	v_pk_fma_f32 v[118:119], v[110:111], v[118:119], s[90:91] op_sel_hi:[1,1,0]
	s_nop 0
	v_pk_fma_f32 v[118:119], v[110:111], v[118:119], s[92:93] op_sel_hi:[1,1,0]
	s_nop 0
	v_pk_mul_f32 v[110:111], v[110:111], v[118:119]
	v_pk_mul_f32 v[118:119], v[106:107], v[106:107]
	v_pk_mul_f32 v[110:111], v[120:121], v[110:111]
	s_nop 0
	v_pk_mul_f32 v[120:121], v[104:105], v[110:111]
	v_pk_fma_f32 v[110:111], v[104:105], v[110:111], v[104:105] neg_lo:[1,0,0] neg_hi:[1,0,0]
	v_and_b32_e32 v104, 0x7fffffff, v106
	v_cndmask_b32_e32 v120, v110, v120, vcc
	v_cmp_gt_f32_e32 vcc, 0, v105
	v_and_b32_e32 v105, 0x7fffffff, v107
	v_pk_fma_f32 v[104:105], v[104:105], s[82:83], 1.0 op_sel_hi:[1,0,0]
	v_cndmask_b32_e32 v121, v111, v121, vcc
	v_rcp_f32_e32 v104, v104
	v_rcp_f32_e32 v105, v105
	v_cmp_gt_f32_e32 vcc, 0, v106
	v_pk_fma_f32 v[110:111], v[104:105], s[84:85], v[108:109] op_sel_hi:[1,0,0]
	s_nop 0
	v_pk_fma_f32 v[110:111], v[104:105], v[110:111], s[88:89] op_sel_hi:[1,1,0]
	s_nop 0
	v_pk_fma_f32 v[110:111], v[104:105], v[110:111], s[90:91] op_sel_hi:[1,1,0]
	s_nop 0
	v_pk_fma_f32 v[110:111], v[104:105], v[110:111], s[92:93] op_sel_hi:[1,1,0]
	s_nop 0
	v_pk_mul_f32 v[104:105], v[104:105], v[110:111]
	v_pk_mul_f32 v[110:111], v[118:119], s[94:95] op_sel_hi:[1,0]
	s_nop 0
	v_exp_f32_e32 v110, v110
	v_exp_f32_e32 v111, v111
	s_nop 0
	v_pk_mul_f32 v[104:105], v[110:111], v[104:105]
	s_nop 0
	v_pk_mul_f32 v[110:111], v[106:107], v[104:105]
	v_pk_fma_f32 v[104:105], v[106:107], v[104:105], v[106:107] neg_lo:[1,0,0] neg_hi:[1,0,0]
	s_nop 0
	v_cndmask_b32_e32 v110, v104, v110, vcc
	v_cmp_gt_f32_e32 vcc, 0, v107
	v_cvt_pk_bf16_f32 v104, v113, v117
	s_nop 1
	v_cndmask_b32_e32 v107, v105, v111, vcc
	v_cvt_pk_bf16_f32 v105, v122, v123
	v_cvt_pk_bf16_f32 v106, v120, v121
	v_cvt_pk_bf16_f32 v107, v110, v107
	global_store_dwordx4 v[114:115], v[104:107], off
	v_pk_mul_f32 v[110:111], v[100:101], v[100:101]
	v_cmp_gt_f32_e32 vcc, 0, v100
	v_and_b32_e32 v105, 0x7fffffff, v101
	v_and_b32_e32 v104, 0x7fffffff, v100
	v_pk_fma_f32 v[104:105], v[104:105], s[82:83], 1.0 op_sel_hi:[1,0,0]
	v_pk_mul_f32 v[110:111], v[110:111], s[94:95] op_sel_hi:[1,0]
; __device__ __forceinline__ unsigned cvt_pk_bf16(float lo, float hi) { unsigned r; asm volatile("v_cvt_pk_bf16_f32 %0, %1, %2" : "=v"(r) : "v"(lo), "v"(hi)); return r; }
; __device__ __forceinline__ f32x2 gelu_pk(f32x2 v) {
;     const f32x2 av = __builtin_elementwise_abs(v), d = av * 0.2316418882f + 1.0f;
;     f32x2 t; t.x = __builtin_amdgcn_rcpf(d.x); t.y = __builtin_amdgcn_rcpf(d.y);
;     f32x2 q = t * 0.5307027145f + (-0.7265760135f); q = q * t + 0.7107068705f; q = q * t + (-0.142248368f); q = q * t + 0.127414796f; q = q * t;
;     const f32x2 s = (v * v) * (-0.72134752044f);
;     f32x2 e; e.x = __builtin_amdgcn_exp2f(s.x); e.y = __builtin_amdgcn_exp2f(s.y);
;     const f32x2 m = v * (q * e), r = v - m;
;     f32x2 o; o.x = v.x < 0.f ? m.x : r.x; o.y = v.y < 0.f ? m.y : r.y; return o;
; }
;     __device__ __forceinline__ void operator()(const f32x4 (&acc)[2][2][4][2], const Unit& u, int wr, int wc, int fr, int fq) const {
;     ...
;             for (int m = 0; m < 4; ++m) { bf16_t* rowp = O + (size_t)(row0 + ai * HALF + m * 16) * ldc + col0;
;                 const float rr = fused ? __builtin_amdgcn_rsqf(ssq[row0 + ai * HALF + m * 16] * inv_n + EPS) : 1.f;
; #pragma unroll
;                 for (int bj = 0; bj < 2; ++bj) { const f32x4 v0 = act4(acc[ai][bj][m][0] * rr + bv[bj][0], ACT), v1 = act4(acc[ai][bj][m][1] * rr + bv[bj][1], ACT);
;                     u32x4 w; w.x = cvt_pk_bf16(v0[0], v0[1]); w.y = cvt_pk_bf16(v0[2], v0[3]); w.z = cvt_pk_bf16(v1[0], v1[1]); w.w = cvt_pk_bf16(v1[2], v1[3]);
;                     *(u32x4*)(rowp + bj * 32) = w; } }
	v_rcp_f32_e32 v104, v104
	v_rcp_f32_e32 v105, v105
	v_exp_f32_e32 v110, v110
	v_exp_f32_e32 v111, v111
	v_pk_fma_f32 v[106:107], v[104:105], s[84:85], v[108:109] op_sel_hi:[1,0,0]
	s_nop 0
	v_pk_fma_f32 v[106:107], v[104:105], v[106:107], s[88:89] op_sel_hi:[1,1,0]
	s_nop 0
	v_pk_fma_f32 v[106:107], v[104:105], v[106:107], s[90:91] op_sel_hi:[1,1,0]
	s_nop 0
	v_pk_fma_f32 v[106:107], v[104:105], v[106:107], s[92:93] op_sel_hi:[1,1,0]
	s_nop 0
	v_pk_mul_f32 v[104:105], v[104:105], v[106:107]
	v_pk_mul_f32 v[106:107], v[102:103], v[102:103]
	v_pk_mul_f32 v[104:105], v[110:111], v[104:105]
	s_nop 0
	v_pk_mul_f32 v[110:111], v[100:101], v[104:105]
	v_pk_fma_f32 v[104:105], v[100:101], v[104:105], v[100:101] neg_lo:[1,0,0] neg_hi:[1,0,0]
	v_and_b32_e32 v100, 0x7fffffff, v102
	v_cndmask_b32_e32 v110, v104, v110, vcc
	v_cmp_gt_f32_e32 vcc, 0, v101
	v_and_b32_e32 v101, 0x7fffffff, v103
	v_pk_fma_f32 v[100:101], v[100:101], s[82:83], 1.0 op_sel_hi:[1,0,0]
	v_cndmask_b32_e32 v111, v105, v111, vcc
	v_rcp_f32_e32 v100, v100
	v_rcp_f32_e32 v101, v101
	v_cmp_gt_f32_e32 vcc, 0, v102
	v_pk_fma_f32 v[104:105], v[100:101], s[84:85], v[108:109] op_sel_hi:[1,0,0]
	s_nop 0
	v_pk_fma_f32 v[104:105], v[100:101], v[104:105], s[88:89] op_sel_hi:[1,1,0]
	s_nop 0
	v_pk_fma_f32 v[104:105], v[100:101], v[104:105], s[90:91] op_sel_hi:[1,1,0]
	s_nop 0
	v_pk_fma_f32 v[104:105], v[100:101], v[104:105], s[92:93] op_sel_hi:[1,1,0]
	s_nop 0
	v_pk_mul_f32 v[100:101], v[100:101], v[104:105]
	v_pk_mul_f32 v[104:105], v[106:107], s[94:95] op_sel_hi:[1,0]
	s_nop 0
	v_exp_f32_e32 v104, v104
	v_exp_f32_e32 v105, v105
	s_nop 0
	v_pk_mul_f32 v[100:101], v[104:105], v[100:101]
	s_nop 0
	v_pk_mul_f32 v[104:105], v[102:103], v[100:101]
	v_pk_fma_f32 v[100:101], v[102:103], v[100:101], v[102:103] neg_lo:[1,0,0] neg_hi:[1,0,0]
	s_nop 0
	v_cndmask_b32_e32 v106, v100, v104, vcc
	v_cmp_gt_f32_e32 vcc, 0, v103
	v_and_b32_e32 v100, 0x7fffffff, v96
	s_nop 0
	v_cndmask_b32_e32 v107, v101, v105, vcc
	v_and_b32_e32 v101, 0x7fffffff, v97
	v_pk_fma_f32 v[100:101], v[100:101], s[82:83], 1.0 op_sel_hi:[1,0,0]
	v_pk_mul_f32 v[104:105], v[96:97], v[96:97]
	v_rcp_f32_e32 v100, v100
	v_rcp_f32_e32 v101, v101
	v_pk_mul_f32 v[104:105], v[104:105], s[94:95] op_sel_hi:[1,0]
	v_cmp_gt_f32_e32 vcc, 0, v96
	v_exp_f32_e32 v104, v104
	v_pk_fma_f32 v[102:103], v[100:101], s[84:85], v[108:109] op_sel_hi:[1,0,0]
	v_exp_f32_e32 v105, v105
	v_pk_fma_f32 v[102:103], v[100:101], v[102:103], s[88:89] op_sel_hi:[1,1,0]
	s_nop 0
	v_pk_fma_f32 v[102:103], v[100:101], v[102:103], s[90:91] op_sel_hi:[1,1,0]
	s_nop 0
	v_pk_fma_f32 v[102:103], v[100:101], v[102:103], s[92:93] op_sel_hi:[1,1,0]
	s_nop 0
	v_pk_mul_f32 v[100:101], v[100:101], v[102:103]
	v_pk_mul_f32 v[102:103], v[98:99], v[98:99]
	v_pk_mul_f32 v[100:101], v[104:105], v[100:101]
	s_nop 0
	v_pk_mul_f32 v[104:105], v[96:97], v[100:101]
	v_pk_fma_f32 v[100:101], v[96:97], v[100:101], v[96:97] neg_lo:[1,0,0] neg_hi:[1,0,0]
	v_and_b32_e32 v96, 0x7fffffff, v98
	v_cndmask_b32_e32 v104, v100, v104, vcc
	v_cmp_gt_f32_e32 vcc, 0, v97
	v_and_b32_e32 v97, 0x7fffffff, v99
	v_pk_fma_f32 v[96:97], v[96:97], s[82:83], 1.0 op_sel_hi:[1,0,0]
	v_cndmask_b32_e32 v105, v101, v105, vcc
	v_rcp_f32_e32 v96, v96
	v_rcp_f32_e32 v97, v97
	v_cmp_gt_f32_e32 vcc, 0, v98
	v_pk_fma_f32 v[100:101], v[96:97], s[84:85], v[108:109] op_sel_hi:[1,0,0]
	s_nop 0
	v_pk_fma_f32 v[100:101], v[96:97], v[100:101], s[88:89] op_sel_hi:[1,1,0]
	s_nop 0
	v_pk_fma_f32 v[100:101], v[96:97], v[100:101], s[90:91] op_sel_hi:[1,1,0]
	s_nop 0
	v_pk_fma_f32 v[100:101], v[96:97], v[100:101], s[92:93] op_sel_hi:[1,1,0]
	s_nop 0
	v_pk_mul_f32 v[96:97], v[96:97], v[100:101]
	v_pk_mul_f32 v[100:101], v[102:103], s[94:95] op_sel_hi:[1,0]
	s_nop 0
	v_exp_f32_e32 v100, v100
	v_exp_f32_e32 v101, v101
	s_nop 0
	v_pk_mul_f32 v[96:97], v[100:101], v[96:97]
	s_nop 0
	v_pk_mul_f32 v[100:101], v[98:99], v[96:97]
	v_pk_fma_f32 v[96:97], v[98:99], v[96:97], v[98:99] neg_lo:[1,0,0] neg_hi:[1,0,0]
	s_nop 0
	v_cndmask_b32_e32 v100, v96, v100, vcc
	v_cmp_gt_f32_e32 vcc, 0, v99
	v_cvt_pk_bf16_f32 v96, v110, v111
	s_nop 1
	v_cndmask_b32_e32 v99, v97, v101, vcc
	v_cvt_pk_bf16_f32 v97, v106, v107
	v_cvt_pk_bf16_f32 v98, v104, v105
	v_cvt_pk_bf16_f32 v99, v100, v99
	global_store_dwordx4 v[114:115], v[96:99], off offset:64
	s_and_b64 vcc, exec, s[8:9]
	s_nop 0
	v_or_b32_e32 v96, 48, v156
	v_ashrrev_i32_e32 v97, 31, v96
	s_cbranch_vccnz .LBB0_294
	v_lshl_add_u64 v[98:99], v[96:97], 2, s[54:55]
	s_nop 2
	v_mov_b32_e32 v98, v249
	v_fmamk_f32 v98, v98, 0x3a800000, v189
	v_rsq_f32_e32 v112, v98
; __device__ __forceinline__ unsigned cvt_pk_bf16(float lo, float hi) { unsigned r; asm volatile("v_cvt_pk_bf16_f32 %0, %1, %2" : "=v"(r) : "v"(lo), "v"(hi)); return r; }
; __device__ __forceinline__ f32x2 gelu_pk(f32x2 v) {
;     const f32x2 av = __builtin_elementwise_abs(v), d = av * 0.2316418882f + 1.0f;
;     f32x2 t; t.x = __builtin_amdgcn_rcpf(d.x); t.y = __builtin_amdgcn_rcpf(d.y);
;     f32x2 q = t * 0.5307027145f + (-0.7265760135f); q = q * t + 0.7107068705f; q = q * t + (-0.142248368f); q = q * t + 0.127414796f; q = q * t;
;     const f32x2 s = (v * v) * (-0.72134752044f);
;     f32x2 e; e.x = __builtin_amdgcn_exp2f(s.x); e.y = __builtin_amdgcn_exp2f(s.y);
;     const f32x2 m = v * (q * e), r = v - m;
;     f32x2 o; o.x = v.x < 0.f ? m.x : r.x; o.y = v.y < 0.f ? m.y : r.y; return o;
; }
;     __device__ __forceinline__ void operator()(const f32x4 (&acc)[2][2][4][2], const Unit& u, int wr, int wc, int fr, int fq) const {
;     ...
;             for (int m = 0; m < 4; ++m) { bf16_t* rowp = O + (size_t)(row0 + ai * HALF + m * 16) * ldc + col0;
;                 const float rr = fused ? __builtin_amdgcn_rsqf(ssq[row0 + ai * HALF + m * 16] * inv_n + EPS) : 1.f;
; #pragma unroll
;                 for (int bj = 0; bj < 2; ++bj) { const f32x4 v0 = act4(acc[ai][bj][m][0] * rr + bv[bj][0], ACT), v1 = act4(acc[ai][bj][m][1] * rr + bv[bj][1], ACT);
;                     u32x4 w; w.x = cvt_pk_bf16(v0[0], v0[1]); w.y = cvt_pk_bf16(v0[2], v0[3]); w.z = cvt_pk_bf16(v1[0], v1[1]); w.w = cvt_pk_bf16(v1[2], v1[3]);
;                     *(u32x4*)(rowp + bj * 32) = w; } }
.LBB0_294:
	s_nop 0
	v_pk_fma_f32 v[98:99], v[92:93], v[112:113], v[44:45] op_sel_hi:[1,0,1]
	v_pk_fma_f32 v[94:95], v[94:95], v[112:113], v[46:47] op_sel_hi:[1,0,1]
	v_and_b32_e32 v93, 0x7fffffff, v99
	v_and_b32_e32 v92, 0x7fffffff, v98
	v_pk_fma_f32 v[92:93], v[92:93], s[82:83], 1.0 op_sel_hi:[1,0,0]
	v_pk_mul_f32 v[104:105], v[98:99], v[98:99]
	v_rcp_f32_e32 v100, v92
	v_rcp_f32_e32 v101, v93
	v_mov_b64_e32 v[92:93], s[70:71]
	v_pk_mul_f32 v[104:105], v[104:105], s[94:95] op_sel_hi:[1,0]
	v_cmp_gt_f32_e32 vcc, 0, v98
	v_pk_fma_f32 v[102:103], v[100:101], s[84:85], v[92:93] op_sel_hi:[1,0,0]
	v_exp_f32_e32 v104, v104
	v_pk_fma_f32 v[102:103], v[100:101], v[102:103], s[88:89] op_sel_hi:[1,1,0]
	v_exp_f32_e32 v105, v105
	v_pk_fma_f32 v[102:103], v[100:101], v[102:103], s[90:91] op_sel_hi:[1,1,0]
	v_pk_fma_f32 v[88:89], v[88:89], v[112:113], v[36:37] op_sel_hi:[1,0,1]
	v_pk_fma_f32 v[102:103], v[100:101], v[102:103], s[92:93] op_sel_hi:[1,1,0]
	v_pk_fma_f32 v[90:91], v[90:91], v[112:113], v[38:39] op_sel_hi:[1,0,1]
	v_pk_mul_f32 v[100:101], v[100:101], v[102:103]
	v_pk_mul_f32 v[102:103], v[94:95], v[94:95]
	v_pk_mul_f32 v[100:101], v[104:105], v[100:101]
	v_lshlrev_b64 v[96:97], 12, v[96:97]
	v_pk_mul_f32 v[104:105], v[98:99], v[100:101]
	v_pk_fma_f32 v[100:101], v[98:99], v[100:101], v[98:99] neg_lo:[1,0,0] neg_hi:[1,0,0]
	v_and_b32_e32 v98, 0x7fffffff, v94
	v_cndmask_b32_e32 v104, v100, v104, vcc
	v_cmp_gt_f32_e32 vcc, 0, v99
	v_and_b32_e32 v99, 0x7fffffff, v95
	v_pk_fma_f32 v[98:99], v[98:99], s[82:83], 1.0 op_sel_hi:[1,0,0]
	v_cndmask_b32_e32 v105, v101, v105, vcc
	v_rcp_f32_e32 v98, v98
	v_rcp_f32_e32 v99, v99
	v_cmp_gt_f32_e32 vcc, 0, v94
	v_lshl_add_u64 v[96:97], s[12:13], 0, v[96:97]
	v_lshl_add_u64 v[96:97], v[154:155], 1, v[96:97]
	v_pk_fma_f32 v[100:101], v[98:99], s[84:85], v[92:93] op_sel_hi:[1,0,0]
	v_pk_fma_f32 v[84:85], v[84:85], v[112:113], v[28:29] op_sel_hi:[1,0,1]
	v_pk_fma_f32 v[100:101], v[98:99], v[100:101], s[88:89] op_sel_hi:[1,1,0]
	v_pk_fma_f32 v[86:87], v[86:87], v[112:113], v[30:31] op_sel_hi:[1,0,1]
	v_pk_fma_f32 v[100:101], v[98:99], v[100:101], s[90:91] op_sel_hi:[1,1,0]
	v_pk_fma_f32 v[80:81], v[80:81], v[112:113], v[24:25] op_sel_hi:[1,0,1]
	v_pk_fma_f32 v[100:101], v[98:99], v[100:101], s[92:93] op_sel_hi:[1,1,0]
	v_pk_fma_f32 v[82:83], v[82:83], v[112:113], v[26:27] op_sel_hi:[1,0,1]
	v_pk_mul_f32 v[98:99], v[98:99], v[100:101]
	v_pk_mul_f32 v[100:101], v[102:103], s[94:95] op_sel_hi:[1,0]
	s_nop 0
	v_exp_f32_e32 v100, v100
	v_exp_f32_e32 v101, v101
	s_nop 0
	v_pk_mul_f32 v[98:99], v[100:101], v[98:99]
	s_nop 0
	v_pk_mul_f32 v[100:101], v[94:95], v[98:99]
	v_pk_fma_f32 v[98:99], v[94:95], v[98:99], v[94:95] neg_lo:[1,0,0] neg_hi:[1,0,0]
	v_and_b32_e32 v94, 0x7fffffff, v88
	v_cndmask_b32_e32 v102, v98, v100, vcc
	v_cmp_gt_f32_e32 vcc, 0, v95
	v_and_b32_e32 v95, 0x7fffffff, v89
	v_pk_fma_f32 v[94:95], v[94:95], s[82:83], 1.0 op_sel_hi:[1,0,0]
	v_cndmask_b32_e32 v103, v99, v101, vcc
	v_rcp_f32_e32 v94, v94
	v_rcp_f32_e32 v95, v95
	v_pk_mul_f32 v[100:101], v[88:89], v[88:89]
	v_cmp_gt_f32_e32 vcc, 0, v88
	v_pk_mul_f32 v[100:101], v[100:101], s[94:95] op_sel_hi:[1,0]
	v_pk_fma_f32 v[98:99], v[94:95], s[84:85], v[92:93] op_sel_hi:[1,0,0]
	v_exp_f32_e32 v100, v100
	v_pk_fma_f32 v[98:99], v[94:95], v[98:99], s[88:89] op_sel_hi:[1,1,0]
	v_exp_f32_e32 v101, v101
	v_pk_fma_f32 v[98:99], v[94:95], v[98:99], s[90:91] op_sel_hi:[1,1,0]
	s_nop 0
	v_pk_fma_f32 v[98:99], v[94:95], v[98:99], s[92:93] op_sel_hi:[1,1,0]
	s_nop 0
	v_pk_mul_f32 v[94:95], v[94:95], v[98:99]
	v_pk_mul_f32 v[98:99], v[90:91], v[90:91]
	v_pk_mul_f32 v[94:95], v[100:101], v[94:95]
	s_nop 0
	v_pk_mul_f32 v[100:101], v[88:89], v[94:95]
	v_pk_fma_f32 v[94:95], v[88:89], v[94:95], v[88:89] neg_lo:[1,0,0] neg_hi:[1,0,0]
	v_and_b32_e32 v88, 0x7fffffff, v90
	v_cndmask_b32_e32 v100, v94, v100, vcc
	v_cmp_gt_f32_e32 vcc, 0, v89
	v_and_b32_e32 v89, 0x7fffffff, v91
	v_pk_fma_f32 v[88:89], v[88:89], s[82:83], 1.0 op_sel_hi:[1,0,0]
	v_cndmask_b32_e32 v101, v95, v101, vcc
	v_rcp_f32_e32 v88, v88
	v_rcp_f32_e32 v89, v89
	v_cmp_gt_f32_e32 vcc, 0, v90
	v_pk_fma_f32 v[94:95], v[88:89], s[84:85], v[92:93] op_sel_hi:[1,0,0]
	s_nop 0
	v_pk_fma_f32 v[94:95], v[88:89], v[94:95], s[88:89] op_sel_hi:[1,1,0]
	s_nop 0
	v_pk_fma_f32 v[94:95], v[88:89], v[94:95], s[90:91] op_sel_hi:[1,1,0]
	s_nop 0
	v_pk_fma_f32 v[94:95], v[88:89], v[94:95], s[92:93] op_sel_hi:[1,1,0]
	s_nop 0
	v_pk_mul_f32 v[88:89], v[88:89], v[94:95]
	v_pk_mul_f32 v[94:95], v[98:99], s[94:95] op_sel_hi:[1,0]
	s_nop 0
	v_exp_f32_e32 v94, v94
	v_exp_f32_e32 v95, v95
	s_nop 0
	v_pk_mul_f32 v[88:89], v[94:95], v[88:89]
	s_nop 0
	v_pk_mul_f32 v[94:95], v[90:91], v[88:89]
	v_pk_fma_f32 v[88:89], v[90:91], v[88:89], v[90:91] neg_lo:[1,0,0] neg_hi:[1,0,0]
	s_nop 0
	v_cndmask_b32_e32 v94, v88, v94, vcc
	v_cmp_gt_f32_e32 vcc, 0, v91
	v_cvt_pk_bf16_f32 v88, v104, v105
	s_nop 1
	v_cndmask_b32_e32 v91, v89, v95, vcc
	v_cvt_pk_bf16_f32 v89, v102, v103
	v_cvt_pk_bf16_f32 v90, v100, v101
	v_cvt_pk_bf16_f32 v91, v94, v91
	global_store_dwordx4 v[96:97], v[88:91], off
	v_pk_mul_f32 v[94:95], v[84:85], v[84:85]
	v_cmp_gt_f32_e32 vcc, 0, v84
	v_and_b32_e32 v89, 0x7fffffff, v85
	v_and_b32_e32 v88, 0x7fffffff, v84
	v_pk_fma_f32 v[88:89], v[88:89], s[82:83], 1.0 op_sel_hi:[1,0,0]
	v_pk_mul_f32 v[94:95], v[94:95], s[94:95] op_sel_hi:[1,0]
	v_rcp_f32_e32 v88, v88
	v_rcp_f32_e32 v89, v89
	v_exp_f32_e32 v94, v94
	v_exp_f32_e32 v95, v95
	v_pk_fma_f32 v[90:91], v[88:89], s[84:85], v[92:93] op_sel_hi:[1,0,0]
	s_nop 0
	v_pk_fma_f32 v[90:91], v[88:89], v[90:91], s[88:89] op_sel_hi:[1,1,0]
	s_nop 0
	v_pk_fma_f32 v[90:91], v[88:89], v[90:91], s[90:91] op_sel_hi:[1,1,0]
; __device__ __forceinline__ unsigned cvt_pk_bf16(float lo, float hi) { unsigned r; asm volatile("v_cvt_pk_bf16_f32 %0, %1, %2" : "=v"(r) : "v"(lo), "v"(hi)); return r; }
; __device__ __forceinline__ f32x2 gelu_pk(f32x2 v) {
;     const f32x2 av = __builtin_elementwise_abs(v), d = av * 0.2316418882f + 1.0f;
;     f32x2 t; t.x = __builtin_amdgcn_rcpf(d.x); t.y = __builtin_amdgcn_rcpf(d.y);
;     f32x2 q = t * 0.5307027145f + (-0.7265760135f); q = q * t + 0.7107068705f; q = q * t + (-0.142248368f); q = q * t + 0.127414796f; q = q * t;
;     const f32x2 s = (v * v) * (-0.72134752044f);
;     f32x2 e; e.x = __builtin_amdgcn_exp2f(s.x); e.y = __builtin_amdgcn_exp2f(s.y);
;     const f32x2 m = v * (q * e), r = v - m;
;     f32x2 o; o.x = v.x < 0.f ? m.x : r.x; o.y = v.y < 0.f ? m.y : r.y; return o;
; }
;     __device__ __forceinline__ void operator()(const f32x4 (&acc)[2][2][4][2], const Unit& u, int wr, int wc, int fr, int fq) const {
;     ...
;             for (int m = 0; m < 4; ++m) { bf16_t* rowp = O + (size_t)(row0 + ai * HALF + m * 16) * ldc + col0;
;                 const float rr = fused ? __builtin_amdgcn_rsqf(ssq[row0 + ai * HALF + m * 16] * inv_n + EPS) : 1.f;
; #pragma unroll
;                 for (int bj = 0; bj < 2; ++bj) { const f32x4 v0 = act4(acc[ai][bj][m][0] * rr + bv[bj][0], ACT), v1 = act4(acc[ai][bj][m][1] * rr + bv[bj][1], ACT);
;                     u32x4 w; w.x = cvt_pk_bf16(v0[0], v0[1]); w.y = cvt_pk_bf16(v0[2], v0[3]); w.z = cvt_pk_bf16(v1[0], v1[1]); w.w = cvt_pk_bf16(v1[2], v1[3]);
;                     *(u32x4*)(rowp + bj * 32) = w; } }
	s_nop 0
	v_pk_fma_f32 v[90:91], v[88:89], v[90:91], s[92:93] op_sel_hi:[1,1,0]
	s_nop 0
	v_pk_mul_f32 v[88:89], v[88:89], v[90:91]
	v_pk_mul_f32 v[90:91], v[86:87], v[86:87]
	v_pk_mul_f32 v[88:89], v[94:95], v[88:89]
	s_nop 0
	v_pk_mul_f32 v[94:95], v[84:85], v[88:89]
	v_pk_fma_f32 v[88:89], v[84:85], v[88:89], v[84:85] neg_lo:[1,0,0] neg_hi:[1,0,0]
	v_and_b32_e32 v84, 0x7fffffff, v86
	v_cndmask_b32_e32 v94, v88, v94, vcc
	v_cmp_gt_f32_e32 vcc, 0, v85
	v_and_b32_e32 v85, 0x7fffffff, v87
	v_pk_fma_f32 v[84:85], v[84:85], s[82:83], 1.0 op_sel_hi:[1,0,0]
	v_cndmask_b32_e32 v95, v89, v95, vcc
	v_rcp_f32_e32 v84, v84
	v_rcp_f32_e32 v85, v85
	v_cmp_gt_f32_e32 vcc, 0, v86
	v_pk_fma_f32 v[88:89], v[84:85], s[84:85], v[92:93] op_sel_hi:[1,0,0]
	s_nop 0
	v_pk_fma_f32 v[88:89], v[84:85], v[88:89], s[88:89] op_sel_hi:[1,1,0]
	s_nop 0
	v_pk_fma_f32 v[88:89], v[84:85], v[88:89], s[90:91] op_sel_hi:[1,1,0]
	s_nop 0
	v_pk_fma_f32 v[88:89], v[84:85], v[88:89], s[92:93] op_sel_hi:[1,1,0]
	s_nop 0
	v_pk_mul_f32 v[84:85], v[84:85], v[88:89]
	v_pk_mul_f32 v[88:89], v[90:91], s[94:95] op_sel_hi:[1,0]
	s_nop 0
	v_exp_f32_e32 v88, v88
	v_exp_f32_e32 v89, v89
	s_nop 0
	v_pk_mul_f32 v[84:85], v[88:89], v[84:85]
	s_nop 0
	v_pk_mul_f32 v[88:89], v[86:87], v[84:85]
	v_pk_fma_f32 v[84:85], v[86:87], v[84:85], v[86:87] neg_lo:[1,0,0] neg_hi:[1,0,0]
	s_nop 0
	v_cndmask_b32_e32 v90, v84, v88, vcc
	v_cmp_gt_f32_e32 vcc, 0, v87
	v_and_b32_e32 v84, 0x7fffffff, v80
	s_nop 0
	v_cndmask_b32_e32 v91, v85, v89, vcc
	v_and_b32_e32 v85, 0x7fffffff, v81
	v_pk_fma_f32 v[84:85], v[84:85], s[82:83], 1.0 op_sel_hi:[1,0,0]
	v_pk_mul_f32 v[88:89], v[80:81], v[80:81]
	v_rcp_f32_e32 v84, v84
	v_rcp_f32_e32 v85, v85
	v_pk_mul_f32 v[88:89], v[88:89], s[94:95] op_sel_hi:[1,0]
	v_cmp_gt_f32_e32 vcc, 0, v80
	v_exp_f32_e32 v88, v88
	v_pk_fma_f32 v[86:87], v[84:85], s[84:85], v[92:93] op_sel_hi:[1,0,0]
	v_exp_f32_e32 v89, v89
	v_pk_fma_f32 v[86:87], v[84:85], v[86:87], s[88:89] op_sel_hi:[1,1,0]
	s_nop 0
	v_pk_fma_f32 v[86:87], v[84:85], v[86:87], s[90:91] op_sel_hi:[1,1,0]
	s_nop 0
	v_pk_fma_f32 v[86:87], v[84:85], v[86:87], s[92:93] op_sel_hi:[1,1,0]
	s_nop 0
	v_pk_mul_f32 v[84:85], v[84:85], v[86:87]
	v_pk_mul_f32 v[86:87], v[82:83], v[82:83]
	v_pk_mul_f32 v[84:85], v[88:89], v[84:85]
	s_nop 0
	v_pk_mul_f32 v[88:89], v[80:81], v[84:85]
	v_pk_fma_f32 v[84:85], v[80:81], v[84:85], v[80:81] neg_lo:[1,0,0] neg_hi:[1,0,0]
	v_and_b32_e32 v80, 0x7fffffff, v82
	v_cndmask_b32_e32 v88, v84, v88, vcc
	v_cmp_gt_f32_e32 vcc, 0, v81
	v_and_b32_e32 v81, 0x7fffffff, v83
	v_pk_fma_f32 v[80:81], v[80:81], s[82:83], 1.0 op_sel_hi:[1,0,0]
	v_cndmask_b32_e32 v89, v85, v89, vcc
	v_rcp_f32_e32 v80, v80
	v_rcp_f32_e32 v81, v81
	v_cmp_gt_f32_e32 vcc, 0, v82
	v_pk_fma_f32 v[84:85], v[80:81], s[84:85], v[92:93] op_sel_hi:[1,0,0]
	s_nop 0
	v_pk_fma_f32 v[84:85], v[80:81], v[84:85], s[88:89] op_sel_hi:[1,1,0]
	s_nop 0
	v_pk_fma_f32 v[84:85], v[80:81], v[84:85], s[90:91] op_sel_hi:[1,1,0]
	s_nop 0
	v_pk_fma_f32 v[84:85], v[80:81], v[84:85], s[92:93] op_sel_hi:[1,1,0]
	s_nop 0
	v_pk_mul_f32 v[80:81], v[80:81], v[84:85]
	v_pk_mul_f32 v[84:85], v[86:87], s[94:95] op_sel_hi:[1,0]
	s_nop 0
	v_exp_f32_e32 v84, v84
	v_exp_f32_e32 v85, v85
	s_nop 0
	v_pk_mul_f32 v[80:81], v[84:85], v[80:81]
	s_nop 0
	v_pk_mul_f32 v[84:85], v[82:83], v[80:81]
	v_pk_fma_f32 v[80:81], v[82:83], v[80:81], v[82:83] neg_lo:[1,0,0] neg_hi:[1,0,0]
	s_nop 0
	v_cndmask_b32_e32 v84, v80, v84, vcc
	v_cmp_gt_f32_e32 vcc, 0, v83
	v_cvt_pk_bf16_f32 v80, v94, v95
	s_nop 1
	v_cndmask_b32_e32 v83, v81, v85, vcc
	v_cvt_pk_bf16_f32 v81, v90, v91
	v_cvt_pk_bf16_f32 v82, v88, v89
	v_cvt_pk_bf16_f32 v83, v84, v83
	global_store_dwordx4 v[96:97], v[80:83], off offset:64
	s_and_b64 vcc, exec, s[8:9]
	v_mov_b32_e32 v84, 1.0
	v_add_u32_e32 v82, 0x80, v156
	v_ashrrev_i32_e32 v83, 31, v82
	v_mov_b32_e32 v80, 1.0
	s_cbranch_vccnz .LBB0_296
	v_lshl_add_u64 v[84:85], v[82:83], 2, s[54:55]
	s_nop 2
	v_mov_b32_e32 v81, v248
	v_fmamk_f32 v81, v81, 0x3a800000, v189
	v_rsq_f32_e32 v84, v81
.LBB0_296:
	s_nop 0
	v_pk_fma_f32 v[86:87], v[76:77], v[84:85], v[44:45] op_sel_hi:[1,0,1]
	v_pk_fma_f32 v[78:79], v[78:79], v[84:85], v[46:47] op_sel_hi:[1,0,1]
	v_and_b32_e32 v77, 0x7fffffff, v87
	v_and_b32_e32 v76, 0x7fffffff, v86
	v_pk_fma_f32 v[76:77], v[76:77], s[82:83], 1.0 op_sel_hi:[1,0,0]
	v_pk_mul_f32 v[92:93], v[86:87], v[86:87]
	v_rcp_f32_e32 v88, v76
	v_rcp_f32_e32 v89, v77
	v_mov_b64_e32 v[76:77], s[70:71]
	v_pk_mul_f32 v[92:93], v[92:93], s[94:95] op_sel_hi:[1,0]
	v_cmp_gt_f32_e32 vcc, 0, v86
	v_pk_fma_f32 v[90:91], v[88:89], s[84:85], v[76:77] op_sel_hi:[1,0,0]
	v_exp_f32_e32 v92, v92
	v_pk_fma_f32 v[90:91], v[88:89], v[90:91], s[88:89] op_sel_hi:[1,1,0]
	v_exp_f32_e32 v93, v93
	v_pk_fma_f32 v[90:91], v[88:89], v[90:91], s[90:91] op_sel_hi:[1,1,0]
	v_lshlrev_b64 v[82:83], 12, v[82:83]
	v_pk_fma_f32 v[90:91], v[88:89], v[90:91], s[92:93] op_sel_hi:[1,1,0]
	v_lshl_add_u64 v[82:83], s[12:13], 0, v[82:83]
	v_pk_mul_f32 v[88:89], v[88:89], v[90:91]
	v_pk_mul_f32 v[90:91], v[78:79], v[78:79]
	v_pk_mul_f32 v[88:89], v[92:93], v[88:89]
	v_lshl_add_u64 v[82:83], v[154:155], 1, v[82:83]
	v_pk_mul_f32 v[92:93], v[86:87], v[88:89]
	v_pk_fma_f32 v[88:89], v[86:87], v[88:89], v[86:87] neg_lo:[1,0,0] neg_hi:[1,0,0]
	v_and_b32_e32 v86, 0x7fffffff, v78
	v_cndmask_b32_e32 v81, v88, v92, vcc
	v_cmp_gt_f32_e32 vcc, 0, v87
	v_and_b32_e32 v87, 0x7fffffff, v79
	v_pk_fma_f32 v[86:87], v[86:87], s[82:83], 1.0 op_sel_hi:[1,0,0]
	v_cndmask_b32_e32 v85, v89, v93, vcc
	v_rcp_f32_e32 v86, v86
	v_rcp_f32_e32 v87, v87
	v_cmp_gt_f32_e32 vcc, 0, v78
	v_pk_fma_f32 v[72:73], v[72:73], v[84:85], v[36:37] op_sel_hi:[1,0,1]
; __device__ __forceinline__ unsigned cvt_pk_bf16(float lo, float hi) { unsigned r; asm volatile("v_cvt_pk_bf16_f32 %0, %1, %2" : "=v"(r) : "v"(lo), "v"(hi)); return r; }
; __device__ __forceinline__ f32x2 gelu_pk(f32x2 v) {
;     const f32x2 av = __builtin_elementwise_abs(v), d = av * 0.2316418882f + 1.0f;
;     f32x2 t; t.x = __builtin_amdgcn_rcpf(d.x); t.y = __builtin_amdgcn_rcpf(d.y);
;     f32x2 q = t * 0.5307027145f + (-0.7265760135f); q = q * t + 0.7107068705f; q = q * t + (-0.142248368f); q = q * t + 0.127414796f; q = q * t;
;     const f32x2 s = (v * v) * (-0.72134752044f);
;     f32x2 e; e.x = __builtin_amdgcn_exp2f(s.x); e.y = __builtin_amdgcn_exp2f(s.y);
;     const f32x2 m = v * (q * e), r = v - m;
;     f32x2 o; o.x = v.x < 0.f ? m.x : r.x; o.y = v.y < 0.f ? m.y : r.y; return o;
; }
;     __device__ __forceinline__ void operator()(const f32x4 (&acc)[2][2][4][2], const Unit& u, int wr, int wc, int fr, int fq) const {
;     ...
;                 for (int bj = 0; bj < 2; ++bj) { const f32x4 v0 = act4(acc[ai][bj][m][0] * rr + bv[bj][0], ACT), v1 = act4(acc[ai][bj][m][1] * rr + bv[bj][1], ACT);
;                     u32x4 w; w.x = cvt_pk_bf16(v0[0], v0[1]); w.y = cvt_pk_bf16(v0[2], v0[3]); w.z = cvt_pk_bf16(v1[0], v1[1]); w.w = cvt_pk_bf16(v1[2], v1[3]);
;                     *(u32x4*)(rowp + bj * 32) = w; } }
	v_pk_fma_f32 v[74:75], v[74:75], v[84:85], v[38:39] op_sel_hi:[1,0,1]
	v_pk_fma_f32 v[88:89], v[86:87], s[84:85], v[76:77] op_sel_hi:[1,0,0]
	v_pk_fma_f32 v[68:69], v[68:69], v[84:85], v[28:29] op_sel_hi:[1,0,1]
	v_pk_fma_f32 v[88:89], v[86:87], v[88:89], s[88:89] op_sel_hi:[1,1,0]
	v_pk_fma_f32 v[70:71], v[70:71], v[84:85], v[30:31] op_sel_hi:[1,0,1]
	v_pk_fma_f32 v[88:89], v[86:87], v[88:89], s[90:91] op_sel_hi:[1,1,0]
	v_pk_fma_f32 v[64:65], v[64:65], v[84:85], v[24:25] op_sel_hi:[1,0,1]
	v_pk_fma_f32 v[88:89], v[86:87], v[88:89], s[92:93] op_sel_hi:[1,1,0]
	v_pk_fma_f32 v[66:67], v[66:67], v[84:85], v[26:27] op_sel_hi:[1,0,1]
	v_pk_mul_f32 v[86:87], v[86:87], v[88:89]
	v_pk_mul_f32 v[88:89], v[90:91], s[94:95] op_sel_hi:[1,0]
	s_nop 0
	v_exp_f32_e32 v88, v88
	v_exp_f32_e32 v89, v89
	s_nop 0
	v_pk_mul_f32 v[86:87], v[88:89], v[86:87]
	s_nop 0
	v_pk_mul_f32 v[88:89], v[78:79], v[86:87]
	v_pk_fma_f32 v[86:87], v[78:79], v[86:87], v[78:79] neg_lo:[1,0,0] neg_hi:[1,0,0]
	v_and_b32_e32 v78, 0x7fffffff, v72
	v_cndmask_b32_e32 v90, v86, v88, vcc
	v_cmp_gt_f32_e32 vcc, 0, v79
	v_and_b32_e32 v79, 0x7fffffff, v73
	v_pk_fma_f32 v[78:79], v[78:79], s[82:83], 1.0 op_sel_hi:[1,0,0]
	v_cndmask_b32_e32 v91, v87, v89, vcc
	v_rcp_f32_e32 v78, v78
	v_rcp_f32_e32 v79, v79
	v_pk_mul_f32 v[88:89], v[72:73], v[72:73]
	v_cmp_gt_f32_e32 vcc, 0, v72
	v_pk_mul_f32 v[88:89], v[88:89], s[94:95] op_sel_hi:[1,0]
	v_pk_fma_f32 v[86:87], v[78:79], s[84:85], v[76:77] op_sel_hi:[1,0,0]
	v_exp_f32_e32 v88, v88
	v_pk_fma_f32 v[86:87], v[78:79], v[86:87], s[88:89] op_sel_hi:[1,1,0]
	v_exp_f32_e32 v89, v89
	v_pk_fma_f32 v[86:87], v[78:79], v[86:87], s[90:91] op_sel_hi:[1,1,0]
	s_nop 0
	v_pk_fma_f32 v[86:87], v[78:79], v[86:87], s[92:93] op_sel_hi:[1,1,0]
	s_nop 0
	v_pk_mul_f32 v[78:79], v[78:79], v[86:87]
	v_pk_mul_f32 v[86:87], v[74:75], v[74:75]
	v_pk_mul_f32 v[78:79], v[88:89], v[78:79]
	s_nop 0
	v_pk_mul_f32 v[88:89], v[72:73], v[78:79]
	v_pk_fma_f32 v[78:79], v[72:73], v[78:79], v[72:73] neg_lo:[1,0,0] neg_hi:[1,0,0]
	v_and_b32_e32 v72, 0x7fffffff, v74
	v_cndmask_b32_e32 v88, v78, v88, vcc
	v_cmp_gt_f32_e32 vcc, 0, v73
	v_and_b32_e32 v73, 0x7fffffff, v75
	v_pk_fma_f32 v[72:73], v[72:73], s[82:83], 1.0 op_sel_hi:[1,0,0]
	v_cndmask_b32_e32 v89, v79, v89, vcc
	v_rcp_f32_e32 v72, v72
	v_rcp_f32_e32 v73, v73
	v_cmp_gt_f32_e32 vcc, 0, v74
	v_pk_fma_f32 v[78:79], v[72:73], s[84:85], v[76:77] op_sel_hi:[1,0,0]
	s_nop 0
	v_pk_fma_f32 v[78:79], v[72:73], v[78:79], s[88:89] op_sel_hi:[1,1,0]
	s_nop 0
	v_pk_fma_f32 v[78:79], v[72:73], v[78:79], s[90:91] op_sel_hi:[1,1,0]
	s_nop 0
	v_pk_fma_f32 v[78:79], v[72:73], v[78:79], s[92:93] op_sel_hi:[1,1,0]
	s_nop 0
	v_pk_mul_f32 v[72:73], v[72:73], v[78:79]
	v_pk_mul_f32 v[78:79], v[86:87], s[94:95] op_sel_hi:[1,0]
	s_nop 0
	v_exp_f32_e32 v78, v78
	v_exp_f32_e32 v79, v79
	s_nop 0
	v_pk_mul_f32 v[72:73], v[78:79], v[72:73]
	s_nop 0
	v_pk_mul_f32 v[78:79], v[74:75], v[72:73]
	v_pk_fma_f32 v[72:73], v[74:75], v[72:73], v[74:75] neg_lo:[1,0,0] neg_hi:[1,0,0]
	s_nop 0
	v_cndmask_b32_e32 v78, v72, v78, vcc
	v_cmp_gt_f32_e32 vcc, 0, v75
	v_cvt_pk_bf16_f32 v72, v81, v85
	s_nop 1
	v_cndmask_b32_e32 v75, v73, v79, vcc
	v_cvt_pk_bf16_f32 v73, v90, v91
	v_cvt_pk_bf16_f32 v74, v88, v89
	v_cvt_pk_bf16_f32 v75, v78, v75
	global_store_dwordx4 v[82:83], v[72:75], off
	v_pk_mul_f32 v[78:79], v[68:69], v[68:69]
	v_cmp_gt_f32_e32 vcc, 0, v68
	v_and_b32_e32 v73, 0x7fffffff, v69
	v_and_b32_e32 v72, 0x7fffffff, v68
	v_pk_fma_f32 v[72:73], v[72:73], s[82:83], 1.0 op_sel_hi:[1,0,0]
	v_pk_mul_f32 v[78:79], v[78:79], s[94:95] op_sel_hi:[1,0]
	v_rcp_f32_e32 v72, v72
	v_rcp_f32_e32 v73, v73
	v_exp_f32_e32 v78, v78
	v_exp_f32_e32 v79, v79
	v_pk_fma_f32 v[74:75], v[72:73], s[84:85], v[76:77] op_sel_hi:[1,0,0]
	s_nop 0
	v_pk_fma_f32 v[74:75], v[72:73], v[74:75], s[88:89] op_sel_hi:[1,1,0]
	s_nop 0
	v_pk_fma_f32 v[74:75], v[72:73], v[74:75], s[90:91] op_sel_hi:[1,1,0]
	s_nop 0
	v_pk_fma_f32 v[74:75], v[72:73], v[74:75], s[92:93] op_sel_hi:[1,1,0]
	s_nop 0
	v_pk_mul_f32 v[72:73], v[72:73], v[74:75]
	v_pk_mul_f32 v[74:75], v[70:71], v[70:71]
	v_pk_mul_f32 v[72:73], v[78:79], v[72:73]
	s_nop 0
	v_pk_mul_f32 v[78:79], v[68:69], v[72:73]
	v_pk_fma_f32 v[72:73], v[68:69], v[72:73], v[68:69] neg_lo:[1,0,0] neg_hi:[1,0,0]
	v_and_b32_e32 v68, 0x7fffffff, v70
	v_cndmask_b32_e32 v78, v72, v78, vcc
	v_cmp_gt_f32_e32 vcc, 0, v69
	v_and_b32_e32 v69, 0x7fffffff, v71
	v_pk_fma_f32 v[68:69], v[68:69], s[82:83], 1.0 op_sel_hi:[1,0,0]
	v_cndmask_b32_e32 v79, v73, v79, vcc
	v_rcp_f32_e32 v68, v68
	v_rcp_f32_e32 v69, v69
	v_cmp_gt_f32_e32 vcc, 0, v70
	v_pk_fma_f32 v[72:73], v[68:69], s[84:85], v[76:77] op_sel_hi:[1,0,0]
	s_nop 0
	v_pk_fma_f32 v[72:73], v[68:69], v[72:73], s[88:89] op_sel_hi:[1,1,0]
	s_nop 0
	v_pk_fma_f32 v[72:73], v[68:69], v[72:73], s[90:91] op_sel_hi:[1,1,0]
	s_nop 0
	v_pk_fma_f32 v[72:73], v[68:69], v[72:73], s[92:93] op_sel_hi:[1,1,0]
	s_nop 0
	v_pk_mul_f32 v[68:69], v[68:69], v[72:73]
	v_pk_mul_f32 v[72:73], v[74:75], s[94:95] op_sel_hi:[1,0]
	s_nop 0
	v_exp_f32_e32 v72, v72
	v_exp_f32_e32 v73, v73
	s_nop 0
	v_pk_mul_f32 v[68:69], v[72:73], v[68:69]
	s_nop 0
	v_pk_mul_f32 v[72:73], v[70:71], v[68:69]
	v_pk_fma_f32 v[68:69], v[70:71], v[68:69], v[70:71] neg_lo:[1,0,0] neg_hi:[1,0,0]
	s_nop 0
	v_cndmask_b32_e32 v74, v68, v72, vcc
	v_cmp_gt_f32_e32 vcc, 0, v71
	v_and_b32_e32 v68, 0x7fffffff, v64
	s_nop 0
	v_cndmask_b32_e32 v75, v69, v73, vcc
	v_and_b32_e32 v69, 0x7fffffff, v65
	v_pk_fma_f32 v[68:69], v[68:69], s[82:83], 1.0 op_sel_hi:[1,0,0]
	v_pk_mul_f32 v[72:73], v[64:65], v[64:65]
	v_rcp_f32_e32 v68, v68
	v_rcp_f32_e32 v69, v69
	v_pk_mul_f32 v[72:73], v[72:73], s[94:95] op_sel_hi:[1,0]
; __device__ __forceinline__ unsigned cvt_pk_bf16(float lo, float hi) { unsigned r; asm volatile("v_cvt_pk_bf16_f32 %0, %1, %2" : "=v"(r) : "v"(lo), "v"(hi)); return r; }
; __device__ __forceinline__ f32x2 gelu_pk(f32x2 v) {
;     const f32x2 av = __builtin_elementwise_abs(v), d = av * 0.2316418882f + 1.0f;
;     f32x2 t; t.x = __builtin_amdgcn_rcpf(d.x); t.y = __builtin_amdgcn_rcpf(d.y);
;     f32x2 q = t * 0.5307027145f + (-0.7265760135f); q = q * t + 0.7107068705f; q = q * t + (-0.142248368f); q = q * t + 0.127414796f; q = q * t;
;     const f32x2 s = (v * v) * (-0.72134752044f);
;     f32x2 e; e.x = __builtin_amdgcn_exp2f(s.x); e.y = __builtin_amdgcn_exp2f(s.y);
;     const f32x2 m = v * (q * e), r = v - m;
;     f32x2 o; o.x = v.x < 0.f ? m.x : r.x; o.y = v.y < 0.f ? m.y : r.y; return o;
; }
;     __device__ __forceinline__ void operator()(const f32x4 (&acc)[2][2][4][2], const Unit& u, int wr, int wc, int fr, int fq) const {
;     ...
;             for (int m = 0; m < 4; ++m) { bf16_t* rowp = O + (size_t)(row0 + ai * HALF + m * 16) * ldc + col0;
;                 const float rr = fused ? __builtin_amdgcn_rsqf(ssq[row0 + ai * HALF + m * 16] * inv_n + EPS) : 1.f;
; #pragma unroll
;                 for (int bj = 0; bj < 2; ++bj) { const f32x4 v0 = act4(acc[ai][bj][m][0] * rr + bv[bj][0], ACT), v1 = act4(acc[ai][bj][m][1] * rr + bv[bj][1], ACT);
;                     u32x4 w; w.x = cvt_pk_bf16(v0[0], v0[1]); w.y = cvt_pk_bf16(v0[2], v0[3]); w.z = cvt_pk_bf16(v1[0], v1[1]); w.w = cvt_pk_bf16(v1[2], v1[3]);
;                     *(u32x4*)(rowp + bj * 32) = w; } }
	v_cmp_gt_f32_e32 vcc, 0, v64
	v_exp_f32_e32 v72, v72
	v_pk_fma_f32 v[70:71], v[68:69], s[84:85], v[76:77] op_sel_hi:[1,0,0]
	v_exp_f32_e32 v73, v73
	v_pk_fma_f32 v[70:71], v[68:69], v[70:71], s[88:89] op_sel_hi:[1,1,0]
	s_nop 0
	v_pk_fma_f32 v[70:71], v[68:69], v[70:71], s[90:91] op_sel_hi:[1,1,0]
	s_nop 0
	v_pk_fma_f32 v[70:71], v[68:69], v[70:71], s[92:93] op_sel_hi:[1,1,0]
	s_nop 0
	v_pk_mul_f32 v[68:69], v[68:69], v[70:71]
	v_pk_mul_f32 v[70:71], v[66:67], v[66:67]
	v_pk_mul_f32 v[68:69], v[72:73], v[68:69]
	s_nop 0
	v_pk_mul_f32 v[72:73], v[64:65], v[68:69]
	v_pk_fma_f32 v[68:69], v[64:65], v[68:69], v[64:65] neg_lo:[1,0,0] neg_hi:[1,0,0]
	v_and_b32_e32 v64, 0x7fffffff, v66
	v_cndmask_b32_e32 v72, v68, v72, vcc
	v_cmp_gt_f32_e32 vcc, 0, v65
	v_and_b32_e32 v65, 0x7fffffff, v67
	v_pk_fma_f32 v[64:65], v[64:65], s[82:83], 1.0 op_sel_hi:[1,0,0]
	v_cndmask_b32_e32 v73, v69, v73, vcc
	v_rcp_f32_e32 v64, v64
	v_rcp_f32_e32 v65, v65
	v_cmp_gt_f32_e32 vcc, 0, v66
	v_pk_fma_f32 v[68:69], v[64:65], s[84:85], v[76:77] op_sel_hi:[1,0,0]
	s_nop 0
	v_pk_fma_f32 v[68:69], v[64:65], v[68:69], s[88:89] op_sel_hi:[1,1,0]
	s_nop 0
	v_pk_fma_f32 v[68:69], v[64:65], v[68:69], s[90:91] op_sel_hi:[1,1,0]
	s_nop 0
	v_pk_fma_f32 v[68:69], v[64:65], v[68:69], s[92:93] op_sel_hi:[1,1,0]
	s_nop 0
	v_pk_mul_f32 v[64:65], v[64:65], v[68:69]
	v_pk_mul_f32 v[68:69], v[70:71], s[94:95] op_sel_hi:[1,0]
	s_nop 0
	v_exp_f32_e32 v68, v68
	v_exp_f32_e32 v69, v69
	s_nop 0
	v_pk_mul_f32 v[64:65], v[68:69], v[64:65]
	s_nop 0
	v_pk_mul_f32 v[68:69], v[66:67], v[64:65]
	v_pk_fma_f32 v[64:65], v[66:67], v[64:65], v[66:67] neg_lo:[1,0,0] neg_hi:[1,0,0]
	s_nop 0
	v_cndmask_b32_e32 v68, v64, v68, vcc
	v_cmp_gt_f32_e32 vcc, 0, v67
	v_cvt_pk_bf16_f32 v64, v78, v79
	s_nop 1
	v_cndmask_b32_e32 v67, v65, v69, vcc
	v_cvt_pk_bf16_f32 v65, v74, v75
	v_cvt_pk_bf16_f32 v66, v72, v73
	v_cvt_pk_bf16_f32 v67, v68, v67
	global_store_dwordx4 v[82:83], v[64:67], off offset:64
	s_and_b64 vcc, exec, s[8:9]
	s_nop 0
	v_add_u32_e32 v64, 0x90, v156
	v_ashrrev_i32_e32 v65, 31, v64
	s_cbranch_vccnz .LBB0_298
	v_lshl_add_u64 v[66:67], v[64:65], 2, s[54:55]
	s_nop 2
	v_mov_b32_e32 v66, v247
	v_fmamk_f32 v66, v66, 0x3a800000, v189
	v_rsq_f32_e32 v80, v66
.LBB0_298:
	s_nop 0
	v_pk_fma_f32 v[66:67], v[60:61], v[80:81], v[44:45] op_sel_hi:[1,0,1]
	v_pk_fma_f32 v[62:63], v[62:63], v[80:81], v[46:47] op_sel_hi:[1,0,1]
	v_and_b32_e32 v61, 0x7fffffff, v67
	v_and_b32_e32 v60, 0x7fffffff, v66
	v_pk_fma_f32 v[60:61], v[60:61], s[82:83], 1.0 op_sel_hi:[1,0,0]
	v_pk_mul_f32 v[72:73], v[66:67], v[66:67]
	v_rcp_f32_e32 v68, v60
	v_rcp_f32_e32 v69, v61
	v_mov_b64_e32 v[60:61], s[70:71]
	v_pk_mul_f32 v[72:73], v[72:73], s[94:95] op_sel_hi:[1,0]
	v_cmp_gt_f32_e32 vcc, 0, v66
	v_pk_fma_f32 v[70:71], v[68:69], s[84:85], v[60:61] op_sel_hi:[1,0,0]
	v_exp_f32_e32 v72, v72
	v_pk_fma_f32 v[70:71], v[68:69], v[70:71], s[88:89] op_sel_hi:[1,1,0]
	v_exp_f32_e32 v73, v73
	v_pk_fma_f32 v[70:71], v[68:69], v[70:71], s[90:91] op_sel_hi:[1,1,0]
	v_pk_fma_f32 v[56:57], v[56:57], v[80:81], v[36:37] op_sel_hi:[1,0,1]
	v_pk_fma_f32 v[70:71], v[68:69], v[70:71], s[92:93] op_sel_hi:[1,1,0]
	v_pk_fma_f32 v[58:59], v[58:59], v[80:81], v[38:39] op_sel_hi:[1,0,1]
	v_pk_mul_f32 v[68:69], v[68:69], v[70:71]
	v_pk_mul_f32 v[70:71], v[62:63], v[62:63]
	v_pk_mul_f32 v[68:69], v[72:73], v[68:69]
	v_lshlrev_b64 v[64:65], 12, v[64:65]
	v_pk_mul_f32 v[72:73], v[66:67], v[68:69]
	v_pk_fma_f32 v[68:69], v[66:67], v[68:69], v[66:67] neg_lo:[1,0,0] neg_hi:[1,0,0]
	v_and_b32_e32 v66, 0x7fffffff, v62
	v_cndmask_b32_e32 v72, v68, v72, vcc
	v_cmp_gt_f32_e32 vcc, 0, v67
	v_and_b32_e32 v67, 0x7fffffff, v63
	v_pk_fma_f32 v[66:67], v[66:67], s[82:83], 1.0 op_sel_hi:[1,0,0]
	v_cndmask_b32_e32 v73, v69, v73, vcc
	v_rcp_f32_e32 v66, v66
	v_rcp_f32_e32 v67, v67
	v_cmp_gt_f32_e32 vcc, 0, v62
	v_lshl_add_u64 v[64:65], s[12:13], 0, v[64:65]
	v_lshl_add_u64 v[64:65], v[154:155], 1, v[64:65]
	v_pk_fma_f32 v[68:69], v[66:67], s[84:85], v[60:61] op_sel_hi:[1,0,0]
	v_pk_fma_f32 v[52:53], v[52:53], v[80:81], v[28:29] op_sel_hi:[1,0,1]
	v_pk_fma_f32 v[68:69], v[66:67], v[68:69], s[88:89] op_sel_hi:[1,1,0]
	v_pk_fma_f32 v[54:55], v[54:55], v[80:81], v[30:31] op_sel_hi:[1,0,1]
	v_pk_fma_f32 v[68:69], v[66:67], v[68:69], s[90:91] op_sel_hi:[1,1,0]
	v_pk_fma_f32 v[48:49], v[48:49], v[80:81], v[24:25] op_sel_hi:[1,0,1]
	v_pk_fma_f32 v[68:69], v[66:67], v[68:69], s[92:93] op_sel_hi:[1,1,0]
	v_pk_fma_f32 v[50:51], v[50:51], v[80:81], v[26:27] op_sel_hi:[1,0,1]
	v_pk_mul_f32 v[66:67], v[66:67], v[68:69]
	v_pk_mul_f32 v[68:69], v[70:71], s[94:95] op_sel_hi:[1,0]
	s_nop 0
	v_exp_f32_e32 v68, v68
	v_exp_f32_e32 v69, v69
	s_nop 0
	v_pk_mul_f32 v[66:67], v[68:69], v[66:67]
	s_nop 0
	v_pk_mul_f32 v[68:69], v[62:63], v[66:67]
	v_pk_fma_f32 v[66:67], v[62:63], v[66:67], v[62:63] neg_lo:[1,0,0] neg_hi:[1,0,0]
	v_and_b32_e32 v62, 0x7fffffff, v56
	v_cndmask_b32_e32 v70, v66, v68, vcc
	v_cmp_gt_f32_e32 vcc, 0, v63
	v_and_b32_e32 v63, 0x7fffffff, v57
	v_pk_fma_f32 v[62:63], v[62:63], s[82:83], 1.0 op_sel_hi:[1,0,0]
	v_cndmask_b32_e32 v71, v67, v69, vcc
	v_rcp_f32_e32 v62, v62
	v_rcp_f32_e32 v63, v63
	v_pk_mul_f32 v[68:69], v[56:57], v[56:57]
	v_cmp_gt_f32_e32 vcc, 0, v56
	v_pk_mul_f32 v[68:69], v[68:69], s[94:95] op_sel_hi:[1,0]
	v_pk_fma_f32 v[66:67], v[62:63], s[84:85], v[60:61] op_sel_hi:[1,0,0]
	v_exp_f32_e32 v68, v68
	v_pk_fma_f32 v[66:67], v[62:63], v[66:67], s[88:89] op_sel_hi:[1,1,0]
	v_exp_f32_e32 v69, v69
	v_pk_fma_f32 v[66:67], v[62:63], v[66:67], s[90:91] op_sel_hi:[1,1,0]
	s_nop 0
	v_pk_fma_f32 v[66:67], v[62:63], v[66:67], s[92:93] op_sel_hi:[1,1,0]
	s_nop 0
	v_pk_mul_f32 v[62:63], v[62:63], v[66:67]
; __device__ __forceinline__ unsigned cvt_pk_bf16(float lo, float hi) { unsigned r; asm volatile("v_cvt_pk_bf16_f32 %0, %1, %2" : "=v"(r) : "v"(lo), "v"(hi)); return r; }
; __device__ __forceinline__ f32x2 gelu_pk(f32x2 v) {
;     const f32x2 av = __builtin_elementwise_abs(v), d = av * 0.2316418882f + 1.0f;
;     f32x2 t; t.x = __builtin_amdgcn_rcpf(d.x); t.y = __builtin_amdgcn_rcpf(d.y);
;     f32x2 q = t * 0.5307027145f + (-0.7265760135f); q = q * t + 0.7107068705f; q = q * t + (-0.142248368f); q = q * t + 0.127414796f; q = q * t;
;     const f32x2 s = (v * v) * (-0.72134752044f);
;     f32x2 e; e.x = __builtin_amdgcn_exp2f(s.x); e.y = __builtin_amdgcn_exp2f(s.y);
;     const f32x2 m = v * (q * e), r = v - m;
;     f32x2 o; o.x = v.x < 0.f ? m.x : r.x; o.y = v.y < 0.f ? m.y : r.y; return o;
; }
;     __device__ __forceinline__ void operator()(const f32x4 (&acc)[2][2][4][2], const Unit& u, int wr, int wc, int fr, int fq) const {
;     ...
;             for (int m = 0; m < 4; ++m) { bf16_t* rowp = O + (size_t)(row0 + ai * HALF + m * 16) * ldc + col0;
;                 const float rr = fused ? __builtin_amdgcn_rsqf(ssq[row0 + ai * HALF + m * 16] * inv_n + EPS) : 1.f;
; #pragma unroll
;                 for (int bj = 0; bj < 2; ++bj) { const f32x4 v0 = act4(acc[ai][bj][m][0] * rr + bv[bj][0], ACT), v1 = act4(acc[ai][bj][m][1] * rr + bv[bj][1], ACT);
;                     u32x4 w; w.x = cvt_pk_bf16(v0[0], v0[1]); w.y = cvt_pk_bf16(v0[2], v0[3]); w.z = cvt_pk_bf16(v1[0], v1[1]); w.w = cvt_pk_bf16(v1[2], v1[3]);
;                     *(u32x4*)(rowp + bj * 32) = w; } }
	v_pk_mul_f32 v[66:67], v[58:59], v[58:59]
	v_pk_mul_f32 v[62:63], v[68:69], v[62:63]
	s_nop 0
	v_pk_mul_f32 v[68:69], v[56:57], v[62:63]
	v_pk_fma_f32 v[62:63], v[56:57], v[62:63], v[56:57] neg_lo:[1,0,0] neg_hi:[1,0,0]
	v_and_b32_e32 v56, 0x7fffffff, v58
	v_cndmask_b32_e32 v68, v62, v68, vcc
	v_cmp_gt_f32_e32 vcc, 0, v57
	v_and_b32_e32 v57, 0x7fffffff, v59
	v_pk_fma_f32 v[56:57], v[56:57], s[82:83], 1.0 op_sel_hi:[1,0,0]
	v_cndmask_b32_e32 v69, v63, v69, vcc
	v_rcp_f32_e32 v56, v56
	v_rcp_f32_e32 v57, v57
	v_cmp_gt_f32_e32 vcc, 0, v58
	v_pk_fma_f32 v[62:63], v[56:57], s[84:85], v[60:61] op_sel_hi:[1,0,0]
	s_nop 0
	v_pk_fma_f32 v[62:63], v[56:57], v[62:63], s[88:89] op_sel_hi:[1,1,0]
	s_nop 0
	v_pk_fma_f32 v[62:63], v[56:57], v[62:63], s[90:91] op_sel_hi:[1,1,0]
	s_nop 0
	v_pk_fma_f32 v[62:63], v[56:57], v[62:63], s[92:93] op_sel_hi:[1,1,0]
	s_nop 0
	v_pk_mul_f32 v[56:57], v[56:57], v[62:63]
	v_pk_mul_f32 v[62:63], v[66:67], s[94:95] op_sel_hi:[1,0]
	s_nop 0
	v_exp_f32_e32 v62, v62
	v_exp_f32_e32 v63, v63
	s_nop 0
	v_pk_mul_f32 v[56:57], v[62:63], v[56:57]
	s_nop 0
	v_pk_mul_f32 v[62:63], v[58:59], v[56:57]
	v_pk_fma_f32 v[56:57], v[58:59], v[56:57], v[58:59] neg_lo:[1,0,0] neg_hi:[1,0,0]
	s_nop 0
	v_cndmask_b32_e32 v62, v56, v62, vcc
	v_cmp_gt_f32_e32 vcc, 0, v59
	v_cvt_pk_bf16_f32 v56, v72, v73
	s_nop 1
	v_cndmask_b32_e32 v59, v57, v63, vcc
	v_cvt_pk_bf16_f32 v57, v70, v71
	v_cvt_pk_bf16_f32 v58, v68, v69
	v_cvt_pk_bf16_f32 v59, v62, v59
	global_store_dwordx4 v[64:65], v[56:59], off
	v_pk_mul_f32 v[62:63], v[52:53], v[52:53]
	v_cmp_gt_f32_e32 vcc, 0, v52
	v_and_b32_e32 v57, 0x7fffffff, v53
	v_and_b32_e32 v56, 0x7fffffff, v52
	v_pk_fma_f32 v[56:57], v[56:57], s[82:83], 1.0 op_sel_hi:[1,0,0]
	v_pk_mul_f32 v[62:63], v[62:63], s[94:95] op_sel_hi:[1,0]
	v_rcp_f32_e32 v56, v56
	v_rcp_f32_e32 v57, v57
	v_exp_f32_e32 v62, v62
	v_exp_f32_e32 v63, v63
	v_pk_fma_f32 v[58:59], v[56:57], s[84:85], v[60:61] op_sel_hi:[1,0,0]
	s_nop 0
	v_pk_fma_f32 v[58:59], v[56:57], v[58:59], s[88:89] op_sel_hi:[1,1,0]
	s_nop 0
	v_pk_fma_f32 v[58:59], v[56:57], v[58:59], s[90:91] op_sel_hi:[1,1,0]
	s_nop 0
	v_pk_fma_f32 v[58:59], v[56:57], v[58:59], s[92:93] op_sel_hi:[1,1,0]
	s_nop 0
	v_pk_mul_f32 v[56:57], v[56:57], v[58:59]
	v_pk_mul_f32 v[58:59], v[54:55], v[54:55]
	v_pk_mul_f32 v[56:57], v[62:63], v[56:57]
	s_nop 0
	v_pk_mul_f32 v[62:63], v[52:53], v[56:57]
	v_pk_fma_f32 v[56:57], v[52:53], v[56:57], v[52:53] neg_lo:[1,0,0] neg_hi:[1,0,0]
	v_and_b32_e32 v52, 0x7fffffff, v54
	v_cndmask_b32_e32 v62, v56, v62, vcc
	v_cmp_gt_f32_e32 vcc, 0, v53
	v_and_b32_e32 v53, 0x7fffffff, v55
	v_pk_fma_f32 v[52:53], v[52:53], s[82:83], 1.0 op_sel_hi:[1,0,0]
	v_cndmask_b32_e32 v63, v57, v63, vcc
	v_rcp_f32_e32 v52, v52
	v_rcp_f32_e32 v53, v53
	v_cmp_gt_f32_e32 vcc, 0, v54
	v_pk_fma_f32 v[56:57], v[52:53], s[84:85], v[60:61] op_sel_hi:[1,0,0]
	s_nop 0
	v_pk_fma_f32 v[56:57], v[52:53], v[56:57], s[88:89] op_sel_hi:[1,1,0]
	s_nop 0
	v_pk_fma_f32 v[56:57], v[52:53], v[56:57], s[90:91] op_sel_hi:[1,1,0]
	s_nop 0
	v_pk_fma_f32 v[56:57], v[52:53], v[56:57], s[92:93] op_sel_hi:[1,1,0]
	s_nop 0
	v_pk_mul_f32 v[52:53], v[52:53], v[56:57]
	v_pk_mul_f32 v[56:57], v[58:59], s[94:95] op_sel_hi:[1,0]
	s_nop 0
	v_exp_f32_e32 v56, v56
	v_exp_f32_e32 v57, v57
	s_nop 0
	v_pk_mul_f32 v[52:53], v[56:57], v[52:53]
	s_nop 0
	v_pk_mul_f32 v[56:57], v[54:55], v[52:53]
	v_pk_fma_f32 v[52:53], v[54:55], v[52:53], v[54:55] neg_lo:[1,0,0] neg_hi:[1,0,0]
	s_nop 0
	v_cndmask_b32_e32 v58, v52, v56, vcc
	v_cmp_gt_f32_e32 vcc, 0, v55
	v_and_b32_e32 v52, 0x7fffffff, v48
	s_nop 0
	v_cndmask_b32_e32 v59, v53, v57, vcc
	v_and_b32_e32 v53, 0x7fffffff, v49
	v_pk_fma_f32 v[52:53], v[52:53], s[82:83], 1.0 op_sel_hi:[1,0,0]
	v_pk_mul_f32 v[56:57], v[48:49], v[48:49]
	v_rcp_f32_e32 v52, v52
	v_rcp_f32_e32 v53, v53
	v_pk_mul_f32 v[56:57], v[56:57], s[94:95] op_sel_hi:[1,0]
	v_cmp_gt_f32_e32 vcc, 0, v48
	v_exp_f32_e32 v56, v56
	v_pk_fma_f32 v[54:55], v[52:53], s[84:85], v[60:61] op_sel_hi:[1,0,0]
	v_exp_f32_e32 v57, v57
	v_pk_fma_f32 v[54:55], v[52:53], v[54:55], s[88:89] op_sel_hi:[1,1,0]
	s_nop 0
	v_pk_fma_f32 v[54:55], v[52:53], v[54:55], s[90:91] op_sel_hi:[1,1,0]
	s_nop 0
	v_pk_fma_f32 v[54:55], v[52:53], v[54:55], s[92:93] op_sel_hi:[1,1,0]
	s_nop 0
	v_pk_mul_f32 v[52:53], v[52:53], v[54:55]
	v_pk_mul_f32 v[54:55], v[50:51], v[50:51]
	v_pk_mul_f32 v[52:53], v[56:57], v[52:53]
	s_nop 0
	v_pk_mul_f32 v[56:57], v[48:49], v[52:53]
	v_pk_fma_f32 v[52:53], v[48:49], v[52:53], v[48:49] neg_lo:[1,0,0] neg_hi:[1,0,0]
	v_and_b32_e32 v48, 0x7fffffff, v50
	v_cndmask_b32_e32 v56, v52, v56, vcc
	v_cmp_gt_f32_e32 vcc, 0, v49
	v_and_b32_e32 v49, 0x7fffffff, v51
	v_pk_fma_f32 v[48:49], v[48:49], s[82:83], 1.0 op_sel_hi:[1,0,0]
	v_cndmask_b32_e32 v57, v53, v57, vcc
	v_rcp_f32_e32 v48, v48
	v_rcp_f32_e32 v49, v49
	v_cmp_gt_f32_e32 vcc, 0, v50
	v_pk_fma_f32 v[52:53], v[48:49], s[84:85], v[60:61] op_sel_hi:[1,0,0]
	s_nop 0
	v_pk_fma_f32 v[52:53], v[48:49], v[52:53], s[88:89] op_sel_hi:[1,1,0]
	s_nop 0
	v_pk_fma_f32 v[52:53], v[48:49], v[52:53], s[90:91] op_sel_hi:[1,1,0]
	s_nop 0
	v_pk_fma_f32 v[52:53], v[48:49], v[52:53], s[92:93] op_sel_hi:[1,1,0]
	s_nop 0
	v_pk_mul_f32 v[48:49], v[48:49], v[52:53]
	v_pk_mul_f32 v[52:53], v[54:55], s[94:95] op_sel_hi:[1,0]
	s_nop 0
	v_exp_f32_e32 v52, v52
	v_exp_f32_e32 v53, v53
	s_nop 0
	v_pk_mul_f32 v[48:49], v[52:53], v[48:49]
	s_nop 0
	v_pk_mul_f32 v[52:53], v[50:51], v[48:49]
	v_pk_fma_f32 v[48:49], v[50:51], v[48:49], v[50:51] neg_lo:[1,0,0] neg_hi:[1,0,0]
	s_nop 0
	v_cndmask_b32_e32 v52, v48, v52, vcc
	v_cmp_gt_f32_e32 vcc, 0, v51
	v_cvt_pk_bf16_f32 v48, v62, v63
	s_nop 1
	v_cndmask_b32_e32 v51, v49, v53, vcc
	v_cvt_pk_bf16_f32 v49, v58, v59
	v_cvt_pk_bf16_f32 v50, v56, v57
	v_cvt_pk_bf16_f32 v51, v52, v51
	global_store_dwordx4 v[64:65], v[48:51], off offset:64
	s_and_b64 vcc, exec, s[8:9]
	v_mov_b32_e32 v52, 1.0
	v_add_u32_e32 v50, 0xa0, v156
	v_ashrrev_i32_e32 v51, 31, v50
	v_mov_b32_e32 v48, 1.0
	s_cbranch_vccnz .LBB0_300
	v_lshl_add_u64 v[52:53], v[50:51], 2, s[54:55]
	s_nop 2
	v_mov_b32_e32 v49, v246
	v_fmamk_f32 v49, v49, 0x3a800000, v189
	v_rsq_f32_e32 v52, v49
; __device__ __forceinline__ unsigned cvt_pk_bf16(float lo, float hi) { unsigned r; asm volatile("v_cvt_pk_bf16_f32 %0, %1, %2" : "=v"(r) : "v"(lo), "v"(hi)); return r; }
; __device__ __forceinline__ f32x2 gelu_pk(f32x2 v) {
;     const f32x2 av = __builtin_elementwise_abs(v), d = av * 0.2316418882f + 1.0f;
;     f32x2 t; t.x = __builtin_amdgcn_rcpf(d.x); t.y = __builtin_amdgcn_rcpf(d.y);
;     f32x2 q = t * 0.5307027145f + (-0.7265760135f); q = q * t + 0.7107068705f; q = q * t + (-0.142248368f); q = q * t + 0.127414796f; q = q * t;
;     const f32x2 s = (v * v) * (-0.72134752044f);
;     f32x2 e; e.x = __builtin_amdgcn_exp2f(s.x); e.y = __builtin_amdgcn_exp2f(s.y);
;     const f32x2 m = v * (q * e), r = v - m;
;     f32x2 o; o.x = v.x < 0.f ? m.x : r.x; o.y = v.y < 0.f ? m.y : r.y; return o;
; }
;     __device__ __forceinline__ void operator()(const f32x4 (&acc)[2][2][4][2], const Unit& u, int wr, int wc, int fr, int fq) const {
;     ...
;             for (int m = 0; m < 4; ++m) { bf16_t* rowp = O + (size_t)(row0 + ai * HALF + m * 16) * ldc + col0;
;                 const float rr = fused ? __builtin_amdgcn_rsqf(ssq[row0 + ai * HALF + m * 16] * inv_n + EPS) : 1.f;
; #pragma unroll
;                 for (int bj = 0; bj < 2; ++bj) { const f32x4 v0 = act4(acc[ai][bj][m][0] * rr + bv[bj][0], ACT), v1 = act4(acc[ai][bj][m][1] * rr + bv[bj][1], ACT);
;                     u32x4 w; w.x = cvt_pk_bf16(v0[0], v0[1]); w.y = cvt_pk_bf16(v0[2], v0[3]); w.z = cvt_pk_bf16(v1[0], v1[1]); w.w = cvt_pk_bf16(v1[2], v1[3]);
;                     *(u32x4*)(rowp + bj * 32) = w; } }
.LBB0_300:
	s_nop 0
	v_pk_fma_f32 v[54:55], v[40:41], v[52:53], v[44:45] op_sel_hi:[1,0,1]
	v_pk_fma_f32 v[42:43], v[42:43], v[52:53], v[46:47] op_sel_hi:[1,0,1]
	v_and_b32_e32 v41, 0x7fffffff, v55
	v_and_b32_e32 v40, 0x7fffffff, v54
	v_pk_fma_f32 v[40:41], v[40:41], s[82:83], 1.0 op_sel_hi:[1,0,0]
	v_pk_mul_f32 v[60:61], v[54:55], v[54:55]
	v_rcp_f32_e32 v56, v40
	v_rcp_f32_e32 v57, v41
	v_mov_b64_e32 v[40:41], s[70:71]
	v_pk_mul_f32 v[60:61], v[60:61], s[94:95] op_sel_hi:[1,0]
	v_cmp_gt_f32_e32 vcc, 0, v54
	v_pk_fma_f32 v[58:59], v[56:57], s[84:85], v[40:41] op_sel_hi:[1,0,0]
	v_exp_f32_e32 v60, v60
	v_pk_fma_f32 v[58:59], v[56:57], v[58:59], s[88:89] op_sel_hi:[1,1,0]
	v_exp_f32_e32 v61, v61
	v_pk_fma_f32 v[58:59], v[56:57], v[58:59], s[90:91] op_sel_hi:[1,1,0]
	v_lshlrev_b64 v[50:51], 12, v[50:51]
	v_pk_fma_f32 v[58:59], v[56:57], v[58:59], s[92:93] op_sel_hi:[1,1,0]
	v_lshl_add_u64 v[50:51], s[12:13], 0, v[50:51]
	v_pk_mul_f32 v[56:57], v[56:57], v[58:59]
	v_pk_mul_f32 v[58:59], v[42:43], v[42:43]
	v_pk_mul_f32 v[56:57], v[60:61], v[56:57]
	v_lshl_add_u64 v[50:51], v[154:155], 1, v[50:51]
	v_pk_mul_f32 v[60:61], v[54:55], v[56:57]
	v_pk_fma_f32 v[56:57], v[54:55], v[56:57], v[54:55] neg_lo:[1,0,0] neg_hi:[1,0,0]
	v_and_b32_e32 v54, 0x7fffffff, v42
	v_cndmask_b32_e32 v49, v56, v60, vcc
	v_cmp_gt_f32_e32 vcc, 0, v55
	v_and_b32_e32 v55, 0x7fffffff, v43
	v_pk_fma_f32 v[54:55], v[54:55], s[82:83], 1.0 op_sel_hi:[1,0,0]
	v_cndmask_b32_e32 v53, v57, v61, vcc
	v_rcp_f32_e32 v54, v54
	v_rcp_f32_e32 v55, v55
	v_cmp_gt_f32_e32 vcc, 0, v42
	v_pk_fma_f32 v[32:33], v[32:33], v[52:53], v[36:37] op_sel_hi:[1,0,1]
	v_pk_fma_f32 v[34:35], v[34:35], v[52:53], v[38:39] op_sel_hi:[1,0,1]
	v_pk_fma_f32 v[56:57], v[54:55], s[84:85], v[40:41] op_sel_hi:[1,0,0]
	v_pk_fma_f32 v[20:21], v[20:21], v[52:53], v[28:29] op_sel_hi:[1,0,1]
	v_pk_fma_f32 v[56:57], v[54:55], v[56:57], s[88:89] op_sel_hi:[1,1,0]
	v_pk_fma_f32 v[22:23], v[22:23], v[52:53], v[30:31] op_sel_hi:[1,0,1]
	v_pk_fma_f32 v[56:57], v[54:55], v[56:57], s[90:91] op_sel_hi:[1,1,0]
	v_pk_fma_f32 v[16:17], v[16:17], v[52:53], v[24:25] op_sel_hi:[1,0,1]
	v_pk_fma_f32 v[56:57], v[54:55], v[56:57], s[92:93] op_sel_hi:[1,1,0]
	v_pk_fma_f32 v[18:19], v[18:19], v[52:53], v[26:27] op_sel_hi:[1,0,1]
	v_pk_mul_f32 v[54:55], v[54:55], v[56:57]
	v_pk_mul_f32 v[56:57], v[58:59], s[94:95] op_sel_hi:[1,0]
	s_nop 0
	v_exp_f32_e32 v56, v56
	v_exp_f32_e32 v57, v57
	s_nop 0
	v_pk_mul_f32 v[54:55], v[56:57], v[54:55]
	s_nop 0
	v_pk_mul_f32 v[56:57], v[42:43], v[54:55]
	v_pk_fma_f32 v[54:55], v[42:43], v[54:55], v[42:43] neg_lo:[1,0,0] neg_hi:[1,0,0]
	v_and_b32_e32 v42, 0x7fffffff, v32
	v_cndmask_b32_e32 v58, v54, v56, vcc
	v_cmp_gt_f32_e32 vcc, 0, v43
	v_and_b32_e32 v43, 0x7fffffff, v33
	v_pk_fma_f32 v[42:43], v[42:43], s[82:83], 1.0 op_sel_hi:[1,0,0]
	v_cndmask_b32_e32 v59, v55, v57, vcc
	v_rcp_f32_e32 v42, v42
	v_rcp_f32_e32 v43, v43
	v_pk_mul_f32 v[56:57], v[32:33], v[32:33]
	v_cmp_gt_f32_e32 vcc, 0, v32
	v_pk_mul_f32 v[56:57], v[56:57], s[94:95] op_sel_hi:[1,0]
	v_pk_fma_f32 v[54:55], v[42:43], s[84:85], v[40:41] op_sel_hi:[1,0,0]
	v_exp_f32_e32 v56, v56
	v_pk_fma_f32 v[54:55], v[42:43], v[54:55], s[88:89] op_sel_hi:[1,1,0]
	v_exp_f32_e32 v57, v57
	v_pk_fma_f32 v[54:55], v[42:43], v[54:55], s[90:91] op_sel_hi:[1,1,0]
	s_nop 0
	v_pk_fma_f32 v[54:55], v[42:43], v[54:55], s[92:93] op_sel_hi:[1,1,0]
	s_nop 0
	v_pk_mul_f32 v[42:43], v[42:43], v[54:55]
	v_pk_mul_f32 v[54:55], v[34:35], v[34:35]
	v_pk_mul_f32 v[42:43], v[56:57], v[42:43]
	s_nop 0
	v_pk_mul_f32 v[56:57], v[32:33], v[42:43]
	v_pk_fma_f32 v[42:43], v[32:33], v[42:43], v[32:33] neg_lo:[1,0,0] neg_hi:[1,0,0]
	v_and_b32_e32 v32, 0x7fffffff, v34
	v_cndmask_b32_e32 v56, v42, v56, vcc
	v_cmp_gt_f32_e32 vcc, 0, v33
	v_and_b32_e32 v33, 0x7fffffff, v35
	v_pk_fma_f32 v[32:33], v[32:33], s[82:83], 1.0 op_sel_hi:[1,0,0]
	v_cndmask_b32_e32 v57, v43, v57, vcc
	v_rcp_f32_e32 v32, v32
	v_rcp_f32_e32 v33, v33
	v_cmp_gt_f32_e32 vcc, 0, v34
	v_pk_fma_f32 v[42:43], v[32:33], s[84:85], v[40:41] op_sel_hi:[1,0,0]
	s_nop 0
	v_pk_fma_f32 v[42:43], v[32:33], v[42:43], s[88:89] op_sel_hi:[1,1,0]
	s_nop 0
	v_pk_fma_f32 v[42:43], v[32:33], v[42:43], s[90:91] op_sel_hi:[1,1,0]
	s_nop 0
	v_pk_fma_f32 v[42:43], v[32:33], v[42:43], s[92:93] op_sel_hi:[1,1,0]
	s_nop 0
	v_pk_mul_f32 v[32:33], v[32:33], v[42:43]
	v_pk_mul_f32 v[42:43], v[54:55], s[94:95] op_sel_hi:[1,0]
	s_nop 0
	v_exp_f32_e32 v42, v42
	v_exp_f32_e32 v43, v43
	s_nop 0
	v_pk_mul_f32 v[32:33], v[42:43], v[32:33]
	s_nop 0
	v_pk_mul_f32 v[42:43], v[34:35], v[32:33]
	v_pk_fma_f32 v[32:33], v[34:35], v[32:33], v[34:35] neg_lo:[1,0,0] neg_hi:[1,0,0]
	s_nop 0
	v_cndmask_b32_e32 v42, v32, v42, vcc
	v_cmp_gt_f32_e32 vcc, 0, v35
	v_cvt_pk_bf16_f32 v32, v49, v53
	s_nop 1
; __device__ __forceinline__ unsigned cvt_pk_bf16(float lo, float hi) { unsigned r; asm volatile("v_cvt_pk_bf16_f32 %0, %1, %2" : "=v"(r) : "v"(lo), "v"(hi)); return r; }
; __device__ __forceinline__ f32x2 gelu_pk(f32x2 v) {
;     const f32x2 av = __builtin_elementwise_abs(v), d = av * 0.2316418882f + 1.0f;
;     f32x2 t; t.x = __builtin_amdgcn_rcpf(d.x); t.y = __builtin_amdgcn_rcpf(d.y);
;     f32x2 q = t * 0.5307027145f + (-0.7265760135f); q = q * t + 0.7107068705f; q = q * t + (-0.142248368f); q = q * t + 0.127414796f; q = q * t;
;     const f32x2 s = (v * v) * (-0.72134752044f);
;     f32x2 e; e.x = __builtin_amdgcn_exp2f(s.x); e.y = __builtin_amdgcn_exp2f(s.y);
;     const f32x2 m = v * (q * e), r = v - m;
;     f32x2 o; o.x = v.x < 0.f ? m.x : r.x; o.y = v.y < 0.f ? m.y : r.y; return o;
; }
;     __device__ __forceinline__ void operator()(const f32x4 (&acc)[2][2][4][2], const Unit& u, int wr, int wc, int fr, int fq) const {
;     ...
;             for (int m = 0; m < 4; ++m) { bf16_t* rowp = O + (size_t)(row0 + ai * HALF + m * 16) * ldc + col0;
;                 const float rr = fused ? __builtin_amdgcn_rsqf(ssq[row0 + ai * HALF + m * 16] * inv_n + EPS) : 1.f;
; #pragma unroll
;                 for (int bj = 0; bj < 2; ++bj) { const f32x4 v0 = act4(acc[ai][bj][m][0] * rr + bv[bj][0], ACT), v1 = act4(acc[ai][bj][m][1] * rr + bv[bj][1], ACT);
;                     u32x4 w; w.x = cvt_pk_bf16(v0[0], v0[1]); w.y = cvt_pk_bf16(v0[2], v0[3]); w.z = cvt_pk_bf16(v1[0], v1[1]); w.w = cvt_pk_bf16(v1[2], v1[3]);
;                     *(u32x4*)(rowp + bj * 32) = w; } }
	v_cndmask_b32_e32 v35, v33, v43, vcc
	v_cvt_pk_bf16_f32 v33, v58, v59
	v_cvt_pk_bf16_f32 v34, v56, v57
	v_cvt_pk_bf16_f32 v35, v42, v35
	global_store_dwordx4 v[50:51], v[32:35], off
	v_pk_mul_f32 v[42:43], v[20:21], v[20:21]
	v_cmp_gt_f32_e32 vcc, 0, v20
	v_and_b32_e32 v33, 0x7fffffff, v21
	v_and_b32_e32 v32, 0x7fffffff, v20
	v_pk_fma_f32 v[32:33], v[32:33], s[82:83], 1.0 op_sel_hi:[1,0,0]
	v_pk_mul_f32 v[42:43], v[42:43], s[94:95] op_sel_hi:[1,0]
	v_rcp_f32_e32 v32, v32
	v_rcp_f32_e32 v33, v33
	v_exp_f32_e32 v42, v42
	v_exp_f32_e32 v43, v43
	v_pk_fma_f32 v[34:35], v[32:33], s[84:85], v[40:41] op_sel_hi:[1,0,0]
	s_nop 0
	v_pk_fma_f32 v[34:35], v[32:33], v[34:35], s[88:89] op_sel_hi:[1,1,0]
	s_nop 0
	v_pk_fma_f32 v[34:35], v[32:33], v[34:35], s[90:91] op_sel_hi:[1,1,0]
	s_nop 0
	v_pk_fma_f32 v[34:35], v[32:33], v[34:35], s[92:93] op_sel_hi:[1,1,0]
	s_nop 0
	v_pk_mul_f32 v[32:33], v[32:33], v[34:35]
	v_pk_mul_f32 v[34:35], v[22:23], v[22:23]
	v_pk_mul_f32 v[32:33], v[42:43], v[32:33]
	s_nop 0
	v_pk_mul_f32 v[42:43], v[20:21], v[32:33]
	v_pk_fma_f32 v[32:33], v[20:21], v[32:33], v[20:21] neg_lo:[1,0,0] neg_hi:[1,0,0]
	v_and_b32_e32 v20, 0x7fffffff, v22
	v_cndmask_b32_e32 v42, v32, v42, vcc
	v_cmp_gt_f32_e32 vcc, 0, v21
	v_and_b32_e32 v21, 0x7fffffff, v23
	v_pk_fma_f32 v[20:21], v[20:21], s[82:83], 1.0 op_sel_hi:[1,0,0]
	v_cndmask_b32_e32 v43, v33, v43, vcc
	v_rcp_f32_e32 v20, v20
	v_rcp_f32_e32 v21, v21
	v_cmp_gt_f32_e32 vcc, 0, v22
	v_pk_fma_f32 v[32:33], v[20:21], s[84:85], v[40:41] op_sel_hi:[1,0,0]
	s_nop 0
	v_pk_fma_f32 v[32:33], v[20:21], v[32:33], s[88:89] op_sel_hi:[1,1,0]
	s_nop 0
	v_pk_fma_f32 v[32:33], v[20:21], v[32:33], s[90:91] op_sel_hi:[1,1,0]
	s_nop 0
	v_pk_fma_f32 v[32:33], v[20:21], v[32:33], s[92:93] op_sel_hi:[1,1,0]
	s_nop 0
	v_pk_mul_f32 v[20:21], v[20:21], v[32:33]
	v_pk_mul_f32 v[32:33], v[34:35], s[94:95] op_sel_hi:[1,0]
	s_nop 0
	v_exp_f32_e32 v32, v32
	v_exp_f32_e32 v33, v33
	s_nop 0
	v_pk_mul_f32 v[20:21], v[32:33], v[20:21]
	s_nop 0
	v_pk_mul_f32 v[32:33], v[22:23], v[20:21]
	v_pk_fma_f32 v[20:21], v[22:23], v[20:21], v[22:23] neg_lo:[1,0,0] neg_hi:[1,0,0]
	s_nop 0
	v_cndmask_b32_e32 v34, v20, v32, vcc
	v_cmp_gt_f32_e32 vcc, 0, v23
	v_and_b32_e32 v20, 0x7fffffff, v16
	s_nop 0
	v_cndmask_b32_e32 v35, v21, v33, vcc
	v_and_b32_e32 v21, 0x7fffffff, v17
	v_pk_fma_f32 v[20:21], v[20:21], s[82:83], 1.0 op_sel_hi:[1,0,0]
	v_pk_mul_f32 v[32:33], v[16:17], v[16:17]
	v_rcp_f32_e32 v20, v20
	v_rcp_f32_e32 v21, v21
	v_pk_mul_f32 v[32:33], v[32:33], s[94:95] op_sel_hi:[1,0]
	v_cmp_gt_f32_e32 vcc, 0, v16
	v_exp_f32_e32 v32, v32
	v_pk_fma_f32 v[22:23], v[20:21], s[84:85], v[40:41] op_sel_hi:[1,0,0]
	v_exp_f32_e32 v33, v33
	v_pk_fma_f32 v[22:23], v[20:21], v[22:23], s[88:89] op_sel_hi:[1,1,0]
	s_nop 0
	v_pk_fma_f32 v[22:23], v[20:21], v[22:23], s[90:91] op_sel_hi:[1,1,0]
	s_nop 0
	v_pk_fma_f32 v[22:23], v[20:21], v[22:23], s[92:93] op_sel_hi:[1,1,0]
	s_nop 0
	v_pk_mul_f32 v[20:21], v[20:21], v[22:23]
	v_pk_mul_f32 v[22:23], v[18:19], v[18:19]
	v_pk_mul_f32 v[20:21], v[32:33], v[20:21]
	s_nop 0
	v_pk_mul_f32 v[32:33], v[16:17], v[20:21]
	v_pk_fma_f32 v[20:21], v[16:17], v[20:21], v[16:17] neg_lo:[1,0,0] neg_hi:[1,0,0]
	v_and_b32_e32 v16, 0x7fffffff, v18
	v_cndmask_b32_e32 v32, v20, v32, vcc
	v_cmp_gt_f32_e32 vcc, 0, v17
	v_and_b32_e32 v17, 0x7fffffff, v19
	v_pk_fma_f32 v[16:17], v[16:17], s[82:83], 1.0 op_sel_hi:[1,0,0]
	v_cndmask_b32_e32 v33, v21, v33, vcc
	v_rcp_f32_e32 v16, v16
	v_rcp_f32_e32 v17, v17
	v_cmp_gt_f32_e32 vcc, 0, v18
	v_pk_fma_f32 v[20:21], v[16:17], s[84:85], v[40:41] op_sel_hi:[1,0,0]
	s_nop 0
	v_pk_fma_f32 v[20:21], v[16:17], v[20:21], s[88:89] op_sel_hi:[1,1,0]
	s_nop 0
	v_pk_fma_f32 v[20:21], v[16:17], v[20:21], s[90:91] op_sel_hi:[1,1,0]
	s_nop 0
	v_pk_fma_f32 v[20:21], v[16:17], v[20:21], s[92:93] op_sel_hi:[1,1,0]
	s_nop 0
	v_pk_mul_f32 v[16:17], v[16:17], v[20:21]
	v_pk_mul_f32 v[20:21], v[22:23], s[94:95] op_sel_hi:[1,0]
	s_nop 0
	v_exp_f32_e32 v20, v20
	v_exp_f32_e32 v21, v21
	s_nop 0
	v_pk_mul_f32 v[16:17], v[20:21], v[16:17]
	s_nop 0
	v_pk_mul_f32 v[20:21], v[18:19], v[16:17]
	v_pk_fma_f32 v[16:17], v[18:19], v[16:17], v[18:19] neg_lo:[1,0,0] neg_hi:[1,0,0]
	s_nop 0
	v_cndmask_b32_e32 v20, v16, v20, vcc
	v_cmp_gt_f32_e32 vcc, 0, v19
	v_cvt_pk_bf16_f32 v16, v42, v43
	s_nop 1
	v_cndmask_b32_e32 v19, v17, v21, vcc
	v_cvt_pk_bf16_f32 v17, v34, v35
	v_cvt_pk_bf16_f32 v18, v32, v33
	v_cvt_pk_bf16_f32 v19, v20, v19
	global_store_dwordx4 v[50:51], v[16:19], off offset:64
	s_and_b64 vcc, exec, s[8:9]
	s_nop 0
	v_add_u32_e32 v16, 0xb0, v156
	v_ashrrev_i32_e32 v17, 31, v16
	s_cbranch_vccnz .LBB0_302
	v_lshl_add_u64 v[18:19], v[16:17], 2, s[54:55]
	s_nop 2
	v_mov_b32_e32 v18, v245
	v_fmamk_f32 v18, v18, 0x3a800000, v189
	v_rsq_f32_e32 v48, v18

;     __device__ __forceinline__ void operator()(const f32x4 (&acc)[2][2][4][2], const Unit& u, int wr, int wc, int fr, int fq) const {
;         const int row0 = u.pm * BM + wr * 64 + fr, col0 = u.pn * BM + wc * 64 + 8 * fq;
;         const bool fused = ssq != nullptr && (all_rows || u.pm < MLAT / BM);
;         f32x4 bv[2][2];
; #pragma unroll
;         for (int bj = 0; bj < 2; ++bj)
; #pragma unroll
;             for (int n = 0; n < 2; ++n) bv[bj][n] = (fused && bias != nullptr) ? *(const f32x4*)(bias + (size_t)(u.pm >> 4) * ldbias + col0 + bj * 32 + 4 * n) : (f32x4){0.f, 0.f, 0.f, 0.f};
; #pragma unroll
;         for (int ai = 0; ai < 2; ++ai)
; #pragma unroll
;             for (int m = 0; m < 4; ++m) { bf16_t* rowp = O + (size_t)(row0 + ai * HALF + m * 16) * ldc + col0;
;                 const float rr = fused ? __builtin_amdgcn_rsqf(ssq[row0 + ai * HALF + m * 16] * inv_n + EPS) : 1.f;
.LBB0_813:
	s_or_b64 exec, exec, s[20:21]
	v_lshl_add_u32 v170, s4, 8, v196
	v_ashrrev_i32_e32 v171, 31, v170
	v_mov_b32_e32 v184, 1.0
	s_and_b64 vcc, exec, s[18:19]
	v_lshl_add_u64 v[178:179], v[170:171], 2, s[54:55]
	s_cbranch_vccnz .LBB0_815
	global_load_dword v251, v[178:179], off offset:64
	global_load_dword v250, v[178:179], off offset:128
	global_load_dword v249, v[178:179], off offset:192
	global_load_dword v248, v[178:179], off offset:512
	global_load_dword v247, v[178:179], off offset:576
	global_load_dword v246, v[178:179], off offset:640
	global_load_dword v245, v[178:179], off offset:704
	global_load_dword v172, v[178:179], off
	s_waitcnt vmcnt(0)
	v_fmamk_f32 v172, v172, 0x3a800000, v189
	v_rsq_f32_e32 v184, v172

;     __device__ __forceinline__ void operator()(const f32x4 (&acc)[2][2][4][2], const Unit& u, int wr, int wc, int fr, int fq) const {
;     ...
;             for (int m = 0; m < 4; ++m) { bf16_t* rowp = O + (size_t)(row0 + ai * HALF + m * 16) * ldc + col0;
;                 const float rr = fused ? __builtin_amdgcn_rsqf(ssq[row0 + ai * HALF + m * 16] * inv_n + EPS) : 1.f;
.LBB0_862:
	s_or_b64 exec, exec, s[4:5]
	s_and_b64 vcc, exec, s[18:19]
	v_mov_b32_e32 v150, 1.0
	s_cbranch_vccnz .LBB0_864
	s_nop 2
	v_mov_b32_e32 v144, v251
	v_fmamk_f32 v144, v144, 0x3a800000, v189
	v_rsq_f32_e32 v150, v144

;     __device__ __forceinline__ void operator()(const f32x4 (&acc)[2][2][4][2], const Unit& u, int wr, int wc, int fr, int fq) const {
;     ...
;             for (int m = 0; m < 4; ++m) { bf16_t* rowp = O + (size_t)(row0 + ai * HALF + m * 16) * ldc + col0;
;                 const float rr = fused ? __builtin_amdgcn_rsqf(ssq[row0 + ai * HALF + m * 16] * inv_n + EPS) : 1.f;
.LBB0_911:
	s_or_b64 exec, exec, s[4:5]
	s_and_b64 vcc, exec, s[18:19]
	v_mov_b32_e32 v134, 1.0
	s_cbranch_vccnz .LBB0_913
	s_nop 2
	v_mov_b32_e32 v128, v250
	v_fmamk_f32 v128, v128, 0x3a800000, v189
	v_rsq_f32_e32 v134, v128

;     __device__ __forceinline__ void operator()(const f32x4 (&acc)[2][2][4][2], const Unit& u, int wr, int wc, int fr, int fq) const {
;     ...
;             for (int m = 0; m < 4; ++m) { bf16_t* rowp = O + (size_t)(row0 + ai * HALF + m * 16) * ldc + col0;
;                 const float rr = fused ? __builtin_amdgcn_rsqf(ssq[row0 + ai * HALF + m * 16] * inv_n + EPS) : 1.f;
.LBB0_960:
	s_or_b64 exec, exec, s[4:5]
	s_and_b64 vcc, exec, s[18:19]
	v_mov_b32_e32 v118, 1.0
	s_cbranch_vccnz .LBB0_962
	s_nop 2
	v_mov_b32_e32 v112, v249
	v_fmamk_f32 v112, v112, 0x3a800000, v189
	v_rsq_f32_e32 v118, v112

;     __device__ __forceinline__ void operator()(const f32x4 (&acc)[2][2][4][2], const Unit& u, int wr, int wc, int fr, int fq) const {
;     ...
;             for (int m = 0; m < 4; ++m) { bf16_t* rowp = O + (size_t)(row0 + ai * HALF + m * 16) * ldc + col0;
;                 const float rr = fused ? __builtin_amdgcn_rsqf(ssq[row0 + ai * HALF + m * 16] * inv_n + EPS) : 1.f;
.LBB0_1009:
	s_or_b64 exec, exec, s[4:5]
	s_and_b64 vcc, exec, s[18:19]
	v_mov_b32_e32 v102, 1.0
	s_cbranch_vccnz .LBB0_1011
	s_nop 2
	v_mov_b32_e32 v96, v248
	v_fmamk_f32 v96, v96, 0x3a800000, v189
	v_rsq_f32_e32 v102, v96

;     __device__ __forceinline__ void operator()(const f32x4 (&acc)[2][2][4][2], const Unit& u, int wr, int wc, int fr, int fq) const {
;     ...
;             for (int m = 0; m < 4; ++m) { bf16_t* rowp = O + (size_t)(row0 + ai * HALF + m * 16) * ldc + col0;
;                 const float rr = fused ? __builtin_amdgcn_rsqf(ssq[row0 + ai * HALF + m * 16] * inv_n + EPS) : 1.f;
.LBB0_1058:
	s_or_b64 exec, exec, s[4:5]
	s_and_b64 vcc, exec, s[18:19]
	v_mov_b32_e32 v86, 1.0
	s_cbranch_vccnz .LBB0_1060
	s_nop 2
	v_mov_b32_e32 v80, v247
	v_fmamk_f32 v80, v80, 0x3a800000, v189
	v_rsq_f32_e32 v86, v80

;     __device__ __forceinline__ void operator()(const f32x4 (&acc)[2][2][4][2], const Unit& u, int wr, int wc, int fr, int fq) const {
;     ...
;             for (int m = 0; m < 4; ++m) { bf16_t* rowp = O + (size_t)(row0 + ai * HALF + m * 16) * ldc + col0;
;                 const float rr = fused ? __builtin_amdgcn_rsqf(ssq[row0 + ai * HALF + m * 16] * inv_n + EPS) : 1.f;
.LBB0_1107:
	s_or_b64 exec, exec, s[4:5]
	s_and_b64 vcc, exec, s[18:19]
	v_mov_b32_e32 v70, 1.0
	s_cbranch_vccnz .LBB0_1109
	s_nop 2
	v_mov_b32_e32 v64, v246
	v_fmamk_f32 v64, v64, 0x3a800000, v189
	v_rsq_f32_e32 v70, v64

;     __device__ __forceinline__ void operator()(const f32x4 (&acc)[2][2][4][2], const Unit& u, int wr, int wc, int fr, int fq) const {
;     ...
;             for (int m = 0; m < 4; ++m) { bf16_t* rowp = O + (size_t)(row0 + ai * HALF + m * 16) * ldc + col0;
;                 const float rr = fused ? __builtin_amdgcn_rsqf(ssq[row0 + ai * HALF + m * 16] * inv_n + EPS) : 1.f;
.LBB0_1156:
	s_or_b64 exec, exec, s[4:5]
	s_and_b64 vcc, exec, s[18:19]
	v_mov_b32_e32 v22, 1.0
	s_cbranch_vccnz .LBB0_1158
	s_nop 2
	v_mov_b32_e32 v16, v245
	v_fmamk_f32 v16, v16, 0x3a800000, v189
	v_rsq_f32_e32 v22, v16

; __device__ __forceinline__ unsigned cvt_pk_bf16(float lo, float hi) { unsigned r; asm volatile("v_cvt_pk_bf16_f32 %0, %1, %2" : "=v"(r) : "v"(lo), "v"(hi)); return r; }
;     __device__ __forceinline__ void operator()(const f32x4 (&acc)[2][2][4][2], const Unit& u, int wr, int wc, int fr, int fq) const {
;     ...
;             for (int m = 0; m < 4; ++m) { bf16_t* rowp = O + (size_t)(row0 + ai * HALF + m * 16) * ldc + col0;
;                 const float rr = fused ? __builtin_amdgcn_rsqf(ssq[row0 + ai * HALF + m * 16] * inv_n + EPS) : 1.f;
; #pragma unroll
;                 for (int bj = 0; bj < 2; ++bj) { const f32x4 v0 = act4(acc[ai][bj][m][0] * rr + bv[bj][0], ACT), v1 = act4(acc[ai][bj][m][1] * rr + bv[bj][1], ACT);
;                     u32x4 w; w.x = cvt_pk_bf16(v0[0], v0[1]); w.y = cvt_pk_bf16(v0[2], v0[3]); w.z = cvt_pk_bf16(v1[0], v1[1]); w.w = cvt_pk_bf16(v1[2], v1[3]);
;                     *(u32x4*)(rowp + bj * 32) = w; } }
.LBB0_1306:
	v_lshl_add_u32 v138, s58, 8, v145
	v_ashrrev_i32_e32 v139, 31, v138
	v_cndmask_b32_e64 v140, 0, 1, s[18:19]
	v_mov_b32_e32 v144, 1.0
	v_cmp_ne_u32_e64 s[8:9], 1, v140
	s_andn2_b64 vcc, exec, s[18:19]
	v_lshl_add_u64 v[140:141], v[138:139], 2, s[10:11]
	v_mov_b32_e32 v146, 1.0
	s_cbranch_vccnz .LBB0_1308
	global_load_dword v251, v[140:141], off offset:64
	global_load_dword v250, v[140:141], off offset:128
	global_load_dword v249, v[140:141], off offset:192
	global_load_dword v248, v[140:141], off offset:512
	global_load_dword v247, v[140:141], off offset:576
	global_load_dword v246, v[140:141], off offset:640
	global_load_dword v245, v[140:141], off offset:704
	global_load_dword v139, v[140:141], off
	s_waitcnt vmcnt(0)
	v_fmamk_f32 v139, v139, 0x3b2aaaab, v189
	v_rsq_f32_e32 v146, v139
.LBB0_1308:
	v_lshl_or_b32 v142, s57, 8, v148
	v_mov_b64_e32 v[150:151], s[16:17]
	v_ashrrev_i32_e32 v143, 31, v142
	v_mad_i64_i32 v[150:151], s[28:29], v138, s89, v[150:151]
	v_lshl_add_u64 v[150:151], v[142:143], 1, v[150:151]
	v_pk_fma_f32 v[126:127], v[126:127], v[146:147], 0 op_sel_hi:[1,0,0]
	v_pk_fma_f32 v[124:125], v[124:125], v[146:147], 0 op_sel_hi:[1,0,0]
	v_pk_fma_f32 v[152:153], v[122:123], v[146:147], 0 op_sel_hi:[1,0,0]
	v_pk_fma_f32 v[122:123], v[120:121], v[146:147], 0 op_sel_hi:[1,0,0]
	v_cvt_pk_bf16_f32 v120, v124, v125
	v_cvt_pk_bf16_f32 v121, v126, v127
	s_and_b64 vcc, exec, s[8:9]
	v_cvt_pk_bf16_f32 v122, v122, v123
	v_cvt_pk_bf16_f32 v123, v152, v153
	global_store_dwordx4 v[150:151], v[120:123], off
	v_pk_fma_f32 v[118:119], v[118:119], v[146:147], 0 op_sel_hi:[1,0,0]
	v_pk_fma_f32 v[116:117], v[116:117], v[146:147], 0 op_sel_hi:[1,0,0]
	v_pk_fma_f32 v[120:121], v[114:115], v[146:147], 0 op_sel_hi:[1,0,0]
	v_pk_fma_f32 v[114:115], v[112:113], v[146:147], 0 op_sel_hi:[1,0,0]
	v_cvt_pk_bf16_f32 v112, v116, v117
	v_cvt_pk_bf16_f32 v113, v118, v119
	s_nop 0
	v_cvt_pk_bf16_f32 v114, v114, v115
	v_cvt_pk_bf16_f32 v115, v120, v121
	global_store_dwordx4 v[150:151], v[112:115], off offset:64
	s_cbranch_vccnz .LBB0_1310
	s_nop 2
	v_mov_b32_e32 v112, v251
	v_fmamk_f32 v112, v112, 0x3b2aaaab, v189
	v_rsq_f32_e32 v144, v112
.LBB0_1310:
	s_nop 0
	v_or_b32_e32 v114, 16, v138
	v_mov_b64_e32 v[112:113], s[16:17]
	v_mad_i64_i32 v[112:113], s[28:29], v114, s89, v[112:113]
	v_lshl_add_u64 v[112:113], v[142:143], 1, v[112:113]
	v_pk_fma_f32 v[110:111], v[110:111], v[144:145], 0 op_sel_hi:[1,0,0]
	v_pk_fma_f32 v[108:109], v[108:109], v[144:145], 0 op_sel_hi:[1,0,0]
	v_pk_fma_f32 v[114:115], v[106:107], v[144:145], 0 op_sel_hi:[1,0,0]
	v_pk_fma_f32 v[106:107], v[104:105], v[144:145], 0 op_sel_hi:[1,0,0]
	v_cvt_pk_bf16_f32 v104, v108, v109
	v_cvt_pk_bf16_f32 v105, v110, v111
	v_pk_fma_f32 v[102:103], v[102:103], v[144:145], 0 op_sel_hi:[1,0,0]
	v_cvt_pk_bf16_f32 v106, v106, v107
	v_cvt_pk_bf16_f32 v107, v114, v115
	global_store_dwordx4 v[112:113], v[104:107], off
	v_pk_fma_f32 v[100:101], v[100:101], v[144:145], 0 op_sel_hi:[1,0,0]
	s_and_b64 vcc, exec, s[8:9]
	v_pk_fma_f32 v[104:105], v[98:99], v[144:145], 0 op_sel_hi:[1,0,0]
	v_pk_fma_f32 v[98:99], v[96:97], v[144:145], 0 op_sel_hi:[1,0,0]
	v_cvt_pk_bf16_f32 v96, v100, v101
	v_cvt_pk_bf16_f32 v97, v102, v103
	s_nop 0
	v_cvt_pk_bf16_f32 v98, v98, v99
	v_cvt_pk_bf16_f32 v99, v104, v105
	global_store_dwordx4 v[112:113], v[96:99], off offset:64
	s_nop 1
	v_mov_b32_e32 v96, 1.0
	v_mov_b32_e32 v98, 1.0
	s_cbranch_vccnz .LBB0_1312
	s_nop 2
	v_mov_b32_e32 v97, v250
	v_fmamk_f32 v97, v97, 0x3b2aaaab, v189
	v_rsq_f32_e32 v98, v97
.LBB0_1312:
	v_or_b32_e32 v97, 32, v138
	v_mov_b64_e32 v[100:101], s[16:17]
	v_mad_i64_i32 v[100:101], s[28:29], v97, s89, v[100:101]
	v_lshl_add_u64 v[100:101], v[142:143], 1, v[100:101]
	v_pk_fma_f32 v[94:95], v[94:95], v[98:99], 0 op_sel_hi:[1,0,0]
	v_pk_fma_f32 v[92:93], v[92:93], v[98:99], 0 op_sel_hi:[1,0,0]
	v_pk_fma_f32 v[102:103], v[90:91], v[98:99], 0 op_sel_hi:[1,0,0]
	v_pk_fma_f32 v[90:91], v[88:89], v[98:99], 0 op_sel_hi:[1,0,0]
	v_cvt_pk_bf16_f32 v88, v92, v93
	v_cvt_pk_bf16_f32 v89, v94, v95
	s_and_b64 vcc, exec, s[8:9]
	v_cvt_pk_bf16_f32 v90, v90, v91
	v_cvt_pk_bf16_f32 v91, v102, v103
	global_store_dwordx4 v[100:101], v[88:91], off
	v_pk_fma_f32 v[86:87], v[86:87], v[98:99], 0 op_sel_hi:[1,0,0]
	v_pk_fma_f32 v[84:85], v[84:85], v[98:99], 0 op_sel_hi:[1,0,0]
	v_pk_fma_f32 v[88:89], v[82:83], v[98:99], 0 op_sel_hi:[1,0,0]
	v_pk_fma_f32 v[82:83], v[80:81], v[98:99], 0 op_sel_hi:[1,0,0]
	v_cvt_pk_bf16_f32 v80, v84, v85
	v_cvt_pk_bf16_f32 v81, v86, v87
	s_nop 0
	v_cvt_pk_bf16_f32 v82, v82, v83
	v_cvt_pk_bf16_f32 v83, v88, v89
	global_store_dwordx4 v[100:101], v[80:83], off offset:64
	s_cbranch_vccnz .LBB0_1314
	s_nop 2
	v_mov_b32_e32 v80, v249
	v_fmamk_f32 v80, v80, 0x3b2aaaab, v189
	v_rsq_f32_e32 v96, v80
; __device__ __forceinline__ unsigned cvt_pk_bf16(float lo, float hi) { unsigned r; asm volatile("v_cvt_pk_bf16_f32 %0, %1, %2" : "=v"(r) : "v"(lo), "v"(hi)); return r; }
;     __device__ __forceinline__ void operator()(const f32x4 (&acc)[2][2][4][2], const Unit& u, int wr, int wc, int fr, int fq) const {
;     ...
;             for (int m = 0; m < 4; ++m) { bf16_t* rowp = O + (size_t)(row0 + ai * HALF + m * 16) * ldc + col0;
;                 const float rr = fused ? __builtin_amdgcn_rsqf(ssq[row0 + ai * HALF + m * 16] * inv_n + EPS) : 1.f;
; #pragma unroll
;                 for (int bj = 0; bj < 2; ++bj) { const f32x4 v0 = act4(acc[ai][bj][m][0] * rr + bv[bj][0], ACT), v1 = act4(acc[ai][bj][m][1] * rr + bv[bj][1], ACT);
;                     u32x4 w; w.x = cvt_pk_bf16(v0[0], v0[1]); w.y = cvt_pk_bf16(v0[2], v0[3]); w.z = cvt_pk_bf16(v1[0], v1[1]); w.w = cvt_pk_bf16(v1[2], v1[3]);
;                     *(u32x4*)(rowp + bj * 32) = w; } }
.LBB0_1314:
	s_nop 0
	v_or_b32_e32 v82, 48, v138
	v_mov_b64_e32 v[80:81], s[16:17]
	v_mad_i64_i32 v[80:81], s[28:29], v82, s89, v[80:81]
	v_lshl_add_u64 v[80:81], v[142:143], 1, v[80:81]
	v_pk_fma_f32 v[78:79], v[78:79], v[96:97], 0 op_sel_hi:[1,0,0]
	v_pk_fma_f32 v[76:77], v[76:77], v[96:97], 0 op_sel_hi:[1,0,0]
	v_pk_fma_f32 v[82:83], v[74:75], v[96:97], 0 op_sel_hi:[1,0,0]
	v_pk_fma_f32 v[74:75], v[72:73], v[96:97], 0 op_sel_hi:[1,0,0]
	v_cvt_pk_bf16_f32 v72, v76, v77
	v_cvt_pk_bf16_f32 v73, v78, v79
	v_pk_fma_f32 v[70:71], v[70:71], v[96:97], 0 op_sel_hi:[1,0,0]
	v_cvt_pk_bf16_f32 v74, v74, v75
	v_cvt_pk_bf16_f32 v75, v82, v83
	global_store_dwordx4 v[80:81], v[72:75], off
	v_pk_fma_f32 v[68:69], v[68:69], v[96:97], 0 op_sel_hi:[1,0,0]
	s_and_b64 vcc, exec, s[8:9]
	v_pk_fma_f32 v[72:73], v[66:67], v[96:97], 0 op_sel_hi:[1,0,0]
	v_pk_fma_f32 v[66:67], v[64:65], v[96:97], 0 op_sel_hi:[1,0,0]
	v_cvt_pk_bf16_f32 v64, v68, v69
	v_cvt_pk_bf16_f32 v65, v70, v71
	s_nop 0
	v_cvt_pk_bf16_f32 v66, v66, v67
	v_cvt_pk_bf16_f32 v67, v72, v73
	global_store_dwordx4 v[80:81], v[64:67], off offset:64
	s_nop 1
	v_mov_b32_e32 v64, 1.0
	v_mov_b32_e32 v66, 1.0
	s_cbranch_vccnz .LBB0_1316
	s_nop 2
	v_mov_b32_e32 v65, v248
	v_fmamk_f32 v65, v65, 0x3b2aaaab, v189
	v_rsq_f32_e32 v66, v65
.LBB0_1316:
	v_add_u32_e32 v65, 0x80, v138
	v_mov_b64_e32 v[68:69], s[16:17]
	v_mad_i64_i32 v[68:69], s[28:29], v65, s89, v[68:69]
	v_lshl_add_u64 v[68:69], v[142:143], 1, v[68:69]
	v_pk_fma_f32 v[62:63], v[62:63], v[66:67], 0 op_sel_hi:[1,0,0]
	v_pk_fma_f32 v[60:61], v[60:61], v[66:67], 0 op_sel_hi:[1,0,0]
	v_pk_fma_f32 v[70:71], v[58:59], v[66:67], 0 op_sel_hi:[1,0,0]
	v_pk_fma_f32 v[58:59], v[56:57], v[66:67], 0 op_sel_hi:[1,0,0]
	v_cvt_pk_bf16_f32 v56, v60, v61
	v_cvt_pk_bf16_f32 v57, v62, v63
	s_and_b64 vcc, exec, s[8:9]
	v_cvt_pk_bf16_f32 v58, v58, v59
	v_cvt_pk_bf16_f32 v59, v70, v71
	global_store_dwordx4 v[68:69], v[56:59], off
	v_pk_fma_f32 v[54:55], v[54:55], v[66:67], 0 op_sel_hi:[1,0,0]
	v_pk_fma_f32 v[52:53], v[52:53], v[66:67], 0 op_sel_hi:[1,0,0]
	v_pk_fma_f32 v[56:57], v[50:51], v[66:67], 0 op_sel_hi:[1,0,0]
	v_pk_fma_f32 v[50:51], v[48:49], v[66:67], 0 op_sel_hi:[1,0,0]
	v_cvt_pk_bf16_f32 v48, v52, v53
	v_cvt_pk_bf16_f32 v49, v54, v55
	s_nop 0
	v_cvt_pk_bf16_f32 v50, v50, v51
	v_cvt_pk_bf16_f32 v51, v56, v57
	global_store_dwordx4 v[68:69], v[48:51], off offset:64
	s_cbranch_vccnz .LBB0_1318
	s_nop 2
	v_mov_b32_e32 v48, v247
	v_fmamk_f32 v48, v48, 0x3b2aaaab, v189
	v_rsq_f32_e32 v64, v48
.LBB0_1318:
	s_nop 0
	v_add_u32_e32 v50, 0x90, v138
	v_mov_b64_e32 v[48:49], s[16:17]
	v_mad_i64_i32 v[48:49], s[28:29], v50, s89, v[48:49]
	v_lshl_add_u64 v[48:49], v[142:143], 1, v[48:49]
	v_pk_fma_f32 v[46:47], v[46:47], v[64:65], 0 op_sel_hi:[1,0,0]
	v_pk_fma_f32 v[44:45], v[44:45], v[64:65], 0 op_sel_hi:[1,0,0]
	v_pk_fma_f32 v[50:51], v[42:43], v[64:65], 0 op_sel_hi:[1,0,0]
	v_pk_fma_f32 v[42:43], v[40:41], v[64:65], 0 op_sel_hi:[1,0,0]
	v_cvt_pk_bf16_f32 v40, v44, v45
	v_cvt_pk_bf16_f32 v41, v46, v47
	v_pk_fma_f32 v[38:39], v[38:39], v[64:65], 0 op_sel_hi:[1,0,0]
	v_cvt_pk_bf16_f32 v42, v42, v43
	v_cvt_pk_bf16_f32 v43, v50, v51
	global_store_dwordx4 v[48:49], v[40:43], off
	v_pk_fma_f32 v[36:37], v[36:37], v[64:65], 0 op_sel_hi:[1,0,0]
	s_and_b64 vcc, exec, s[8:9]
	v_pk_fma_f32 v[40:41], v[34:35], v[64:65], 0 op_sel_hi:[1,0,0]
	v_pk_fma_f32 v[34:35], v[32:33], v[64:65], 0 op_sel_hi:[1,0,0]
	v_cvt_pk_bf16_f32 v32, v36, v37
	v_cvt_pk_bf16_f32 v33, v38, v39
	s_nop 0
	v_cvt_pk_bf16_f32 v34, v34, v35
	v_cvt_pk_bf16_f32 v35, v40, v41
	global_store_dwordx4 v[48:49], v[32:35], off offset:64
	s_nop 1
	v_mov_b32_e32 v32, 1.0
	v_mov_b32_e32 v34, 1.0
	s_cbranch_vccnz .LBB0_1320
	s_nop 2
	v_mov_b32_e32 v33, v246
	v_fmamk_f32 v33, v33, 0x3b2aaaab, v189
	v_rsq_f32_e32 v34, v33
.LBB0_1320:
	v_add_u32_e32 v33, 0xa0, v138
	v_mov_b64_e32 v[36:37], s[16:17]
	v_mad_i64_i32 v[36:37], s[28:29], v33, s89, v[36:37]
	v_lshl_add_u64 v[36:37], v[142:143], 1, v[36:37]
	v_pk_fma_f32 v[30:31], v[30:31], v[34:35], 0 op_sel_hi:[1,0,0]
	v_pk_fma_f32 v[28:29], v[28:29], v[34:35], 0 op_sel_hi:[1,0,0]
	v_pk_fma_f32 v[38:39], v[26:27], v[34:35], 0 op_sel_hi:[1,0,0]
	v_pk_fma_f32 v[26:27], v[24:25], v[34:35], 0 op_sel_hi:[1,0,0]
	v_cvt_pk_bf16_f32 v24, v28, v29
	v_cvt_pk_bf16_f32 v25, v30, v31
	s_and_b64 vcc, exec, s[8:9]
	v_cvt_pk_bf16_f32 v26, v26, v27
	v_cvt_pk_bf16_f32 v27, v38, v39
	global_store_dwordx4 v[36:37], v[24:27], off
	v_pk_fma_f32 v[22:23], v[22:23], v[34:35], 0 op_sel_hi:[1,0,0]
	v_pk_fma_f32 v[20:21], v[20:21], v[34:35], 0 op_sel_hi:[1,0,0]
	v_pk_fma_f32 v[24:25], v[18:19], v[34:35], 0 op_sel_hi:[1,0,0]
	v_pk_fma_f32 v[18:19], v[16:17], v[34:35], 0 op_sel_hi:[1,0,0]
	v_cvt_pk_bf16_f32 v16, v20, v21
	v_cvt_pk_bf16_f32 v17, v22, v23
	s_nop 0
	v_cvt_pk_bf16_f32 v18, v18, v19
	v_cvt_pk_bf16_f32 v19, v24, v25
	global_store_dwordx4 v[36:37], v[16:19], off offset:64
	s_cbranch_vccnz .LBB0_1322
	s_nop 2
	v_mov_b32_e32 v16, v245
	v_fmamk_f32 v16, v16, 0x3b2aaaab, v189
	v_rsq_f32_e32 v32, v16

; __device__ __forceinline__ float shx(float v, int o, int lane) { return __int_as_float(__builtin_amdgcn_ds_bpermute((lane ^ o) << 2, __float_as_int(v))); }
;     __device__ __forceinline__ void operator()(const f32x4 (&acc)[2][2][4][2], const Unit& u, int wr, int wc, int fr, int fq) const {
;     ...
;             for (int m = 0; m < 4; ++m) { rl[ai][m] = __builtin_amdgcn_rsqf(ssq_kv[row0 + ai * HALF + m * 16] * (1.f / KVLORA) + EPS);
;                 const f32x4 a0 = acc[ai][0][m][0] * rl[ai][m], a1 = acc[ai][0][m][1] * rl[ai][m];
;                 float s = ((a0[0] * a0[0] + a0[1] * a0[1]) + (a0[2] * a0[2] + a0[3] * a0[3])) + ((a1[0] * a1[0] + a1[1] * a1[1]) + (a1[2] * a1[2] + a1[3] * a1[3]));
;                 s += shx(s, 16, lane); s += shx(s, 32, lane);
;                 if (fq == 0) scr[(ai * HALF + rowl0 + m * 16) * 4 + wc] = s; }
.LBB0_1340:
	v_lshl_add_u32 v166, s36, 8, v187
	v_ashrrev_i32_e32 v167, 31, v166
	v_lshl_add_u64 v[64:65], v[166:167], 2, s[18:19]
	global_load_dword v251, v[64:65], off offset:64
	global_load_dword v250, v[64:65], off offset:128
	global_load_dword v249, v[64:65], off offset:192
	global_load_dword v248, v[64:65], off offset:512
	global_load_dword v247, v[64:65], off offset:576
	global_load_dword v246, v[64:65], off offset:640
	global_load_dword v245, v[64:65], off offset:704
	global_load_dword v66, v[64:65], off
	s_waitcnt vmcnt(0)
	v_fmamk_f32 v66, v66, 0x3b800000, v189
	v_rsq_f32_e32 v184, v66
	s_nop 0
	v_pk_mul_f32 v[66:67], v[134:135], v[184:185] op_sel_hi:[1,0]
	v_pk_mul_f32 v[68:69], v[132:133], v[184:185] op_sel_hi:[1,0]
	v_pk_mul_f32 v[70:71], v[130:131], v[184:185] op_sel_hi:[1,0]
	v_pk_mul_f32 v[156:157], v[128:129], v[184:185] op_sel_hi:[1,0]
	v_mul_f32_e32 v69, v69, v69
	v_mul_f32_e32 v67, v67, v67
	v_mul_f32_e32 v157, v157, v157
	v_mul_f32_e32 v71, v71, v71
	v_fmac_f32_e32 v69, v68, v68
	v_fmac_f32_e32 v67, v66, v66
	v_fmac_f32_e32 v157, v156, v156
	v_fmac_f32_e32 v71, v70, v70
	v_add_f32_e32 v66, v69, v67
	v_add_f32_e32 v67, v157, v71
	v_add_f32_e32 v66, v66, v67
	ds_bpermute_b32 v67, v197, v66
	s_waitcnt lgkmcnt(0)
	v_add_f32_e32 v67, v66, v67
	ds_bpermute_b32 v68, v198, v67
	v_add_u32_e32 v66, s75, v199
	s_and_saveexec_b64 s[36:37], s[6:7]
	s_cbranch_execz .LBB0_1342
	s_waitcnt lgkmcnt(0)
	v_add_f32_e32 v67, v67, v68
	ds_write_b32 v66, v67
.LBB0_1342:
	s_or_b64 exec, exec, s[36:37]
	s_nop 2
	v_mov_b32_e32 v67, v251
	v_fmamk_f32 v67, v67, 0x3b800000, v189
	v_rsq_f32_e32 v182, v67
	s_waitcnt lgkmcnt(0)
	v_pk_mul_f32 v[68:69], v[118:119], v[182:183] op_sel_hi:[1,0]
	v_pk_mul_f32 v[70:71], v[116:117], v[182:183] op_sel_hi:[1,0]
	v_pk_mul_f32 v[156:157], v[114:115], v[182:183] op_sel_hi:[1,0]
	v_pk_mul_f32 v[158:159], v[112:113], v[182:183] op_sel_hi:[1,0]
	v_mul_f32_e32 v67, v71, v71
	v_mul_f32_e32 v69, v69, v69
	v_mul_f32_e32 v71, v159, v159
	v_mul_f32_e32 v157, v157, v157
	v_fmac_f32_e32 v67, v70, v70
	v_fmac_f32_e32 v69, v68, v68
	v_fmac_f32_e32 v71, v158, v158
	v_fmac_f32_e32 v157, v156, v156
	v_add_f32_e32 v67, v67, v69
	v_add_f32_e32 v68, v71, v157
	v_add_f32_e32 v67, v67, v68
	ds_bpermute_b32 v68, v197, v67
	s_waitcnt lgkmcnt(0)
	v_add_f32_e32 v67, v67, v68
	ds_bpermute_b32 v68, v198, v67
	s_and_saveexec_b64 s[36:37], s[6:7]
	s_cbranch_execz .LBB0_1344
	s_waitcnt lgkmcnt(0)
	v_add_f32_e32 v67, v67, v68
	ds_write_b32 v66, v67 offset:256
.LBB0_1344:
	s_or_b64 exec, exec, s[36:37]
	s_nop 2
	v_mov_b32_e32 v67, v250
	v_fmamk_f32 v67, v67, 0x3b800000, v189
	v_rsq_f32_e32 v180, v67
	s_waitcnt lgkmcnt(0)
	v_pk_mul_f32 v[68:69], v[102:103], v[180:181] op_sel_hi:[1,0]
	v_pk_mul_f32 v[70:71], v[100:101], v[180:181] op_sel_hi:[1,0]
	v_pk_mul_f32 v[156:157], v[98:99], v[180:181] op_sel_hi:[1,0]
	v_pk_mul_f32 v[158:159], v[96:97], v[180:181] op_sel_hi:[1,0]
	v_mul_f32_e32 v67, v71, v71
	v_mul_f32_e32 v69, v69, v69
	v_mul_f32_e32 v71, v159, v159
	v_mul_f32_e32 v157, v157, v157
	v_fmac_f32_e32 v67, v70, v70
	v_fmac_f32_e32 v69, v68, v68
	v_fmac_f32_e32 v71, v158, v158
	v_fmac_f32_e32 v157, v156, v156
	v_add_f32_e32 v67, v67, v69
	v_add_f32_e32 v68, v71, v157
	v_add_f32_e32 v67, v67, v68
	ds_bpermute_b32 v68, v197, v67
	s_waitcnt lgkmcnt(0)
	v_add_f32_e32 v67, v67, v68
	ds_bpermute_b32 v68, v198, v67
	s_and_saveexec_b64 s[36:37], s[6:7]
	v_readlane_b32 s76, v255, 3
	v_readlane_b32 s77, v255, 4
	v_readlane_b32 s78, v255, 5
	s_movk_i32 s83, 0x4000
	s_movk_i32 s89, 0xc00
	s_mov_b32 s85, 0x1000000
	s_mov_b32 s86, 0x1400000
	s_mov_b32 s87, 0x1800000
	s_mov_b32 s93, 0x1c00000
	s_mov_b32 s91, 0xf800000
	v_readlane_b32 s79, v255, 6
	s_cbranch_execz .LBB0_1346
	s_waitcnt lgkmcnt(0)
	v_add_f32_e32 v67, v67, v68
	ds_write_b32 v66, v67 offset:512
.LBB0_1346:
	s_or_b64 exec, exec, s[36:37]
	s_nop 2
	v_mov_b32_e32 v67, v249
	v_fmamk_f32 v67, v67, 0x3b800000, v189
	v_rsq_f32_e32 v170, v67
	s_waitcnt lgkmcnt(0)
	v_pk_mul_f32 v[68:69], v[86:87], v[170:171] op_sel_hi:[1,0]
	v_pk_mul_f32 v[70:71], v[84:85], v[170:171] op_sel_hi:[1,0]
	v_pk_mul_f32 v[156:157], v[82:83], v[170:171] op_sel_hi:[1,0]
	v_pk_mul_f32 v[158:159], v[80:81], v[170:171] op_sel_hi:[1,0]
	v_mul_f32_e32 v67, v71, v71
	v_mul_f32_e32 v69, v69, v69
	v_mul_f32_e32 v71, v159, v159
	v_mul_f32_e32 v157, v157, v157
	v_fmac_f32_e32 v67, v70, v70
	v_fmac_f32_e32 v69, v68, v68
	v_fmac_f32_e32 v71, v158, v158
	v_fmac_f32_e32 v157, v156, v156
	v_add_f32_e32 v67, v67, v69
	v_add_f32_e32 v68, v71, v157
	v_add_f32_e32 v67, v67, v68
	ds_bpermute_b32 v68, v197, v67
	s_waitcnt lgkmcnt(0)
	v_add_f32_e32 v67, v67, v68
	ds_bpermute_b32 v68, v198, v67
	s_and_saveexec_b64 s[36:37], s[6:7]
	s_cbranch_execz .LBB0_1348
	s_waitcnt lgkmcnt(0)
	v_add_f32_e32 v67, v67, v68
	ds_write_b32 v66, v67 offset:768
; __device__ __forceinline__ float shx(float v, int o, int lane) { return __int_as_float(__builtin_amdgcn_ds_bpermute((lane ^ o) << 2, __float_as_int(v))); }
;     __device__ __forceinline__ void operator()(const f32x4 (&acc)[2][2][4][2], const Unit& u, int wr, int wc, int fr, int fq) const {
;     ...
;             for (int m = 0; m < 4; ++m) { rl[ai][m] = __builtin_amdgcn_rsqf(ssq_kv[row0 + ai * HALF + m * 16] * (1.f / KVLORA) + EPS);
;                 const f32x4 a0 = acc[ai][0][m][0] * rl[ai][m], a1 = acc[ai][0][m][1] * rl[ai][m];
;                 float s = ((a0[0] * a0[0] + a0[1] * a0[1]) + (a0[2] * a0[2] + a0[3] * a0[3])) + ((a1[0] * a1[0] + a1[1] * a1[1]) + (a1[2] * a1[2] + a1[3] * a1[3]));
;                 s += shx(s, 16, lane); s += shx(s, 32, lane);
;                 if (fq == 0) scr[(ai * HALF + rowl0 + m * 16) * 4 + wc] = s; }
.LBB0_1348:
	s_or_b64 exec, exec, s[36:37]
	s_nop 2
	v_mov_b32_e32 v67, v248
	v_fmamk_f32 v67, v67, 0x3b800000, v189
	v_rsq_f32_e32 v168, v67
	s_waitcnt lgkmcnt(0)
	v_pk_mul_f32 v[68:69], v[58:59], v[168:169] op_sel_hi:[1,0]
	v_pk_mul_f32 v[70:71], v[56:57], v[168:169] op_sel_hi:[1,0]
	v_pk_mul_f32 v[156:157], v[50:51], v[168:169] op_sel_hi:[1,0]
	v_pk_mul_f32 v[158:159], v[48:49], v[168:169] op_sel_hi:[1,0]
	v_mul_f32_e32 v67, v71, v71
	v_mul_f32_e32 v69, v69, v69
	v_mul_f32_e32 v71, v159, v159
	v_mul_f32_e32 v157, v157, v157
	v_fmac_f32_e32 v67, v70, v70
	v_fmac_f32_e32 v69, v68, v68
	v_fmac_f32_e32 v71, v158, v158
	v_fmac_f32_e32 v157, v156, v156
	v_add_f32_e32 v67, v67, v69
	v_add_f32_e32 v68, v71, v157
	v_add_f32_e32 v67, v67, v68
	ds_bpermute_b32 v68, v197, v67
	s_waitcnt lgkmcnt(0)
	v_add_f32_e32 v67, v67, v68
	ds_bpermute_b32 v68, v198, v67
	s_and_saveexec_b64 s[36:37], s[6:7]
	s_cbranch_execz .LBB0_1350
	s_waitcnt lgkmcnt(0)
	v_add_f32_e32 v67, v67, v68
	ds_write_b32 v66, v67 offset:2048
.LBB0_1350:
	s_or_b64 exec, exec, s[36:37]
	s_nop 2
	v_mov_b32_e32 v67, v247
	v_fmamk_f32 v67, v67, 0x3b800000, v189
	v_rsq_f32_e32 v164, v67
	s_waitcnt lgkmcnt(0)
	v_pk_mul_f32 v[68:69], v[46:47], v[164:165] op_sel_hi:[1,0]
	v_pk_mul_f32 v[70:71], v[44:45], v[164:165] op_sel_hi:[1,0]
	v_pk_mul_f32 v[156:157], v[42:43], v[164:165] op_sel_hi:[1,0]
	v_pk_mul_f32 v[158:159], v[40:41], v[164:165] op_sel_hi:[1,0]
	v_mul_f32_e32 v67, v71, v71
	v_mul_f32_e32 v69, v69, v69
	v_mul_f32_e32 v71, v159, v159
	v_mul_f32_e32 v157, v157, v157
	v_fmac_f32_e32 v67, v70, v70
	v_fmac_f32_e32 v69, v68, v68
	v_fmac_f32_e32 v71, v158, v158
	v_fmac_f32_e32 v157, v156, v156
	v_add_f32_e32 v67, v67, v69
	v_add_f32_e32 v68, v71, v157
	v_add_f32_e32 v67, v67, v68
	ds_bpermute_b32 v68, v197, v67
	s_waitcnt lgkmcnt(0)
	v_add_f32_e32 v67, v67, v68
	ds_bpermute_b32 v68, v198, v67
	s_and_saveexec_b64 s[36:37], s[6:7]
	s_cbranch_execz .LBB0_1352
	s_waitcnt lgkmcnt(0)
	v_add_f32_e32 v67, v67, v68
	ds_write_b32 v66, v67 offset:2304
.LBB0_1352:
	s_or_b64 exec, exec, s[36:37]
	s_nop 2
	v_mov_b32_e32 v67, v246
	v_fmamk_f32 v67, v67, 0x3b800000, v189
	v_rsq_f32_e32 v162, v67
	s_waitcnt lgkmcnt(0)
	v_pk_mul_f32 v[68:69], v[30:31], v[162:163] op_sel_hi:[1,0]
	v_pk_mul_f32 v[70:71], v[28:29], v[162:163] op_sel_hi:[1,0]
	v_pk_mul_f32 v[156:157], v[26:27], v[162:163] op_sel_hi:[1,0]
	v_pk_mul_f32 v[158:159], v[24:25], v[162:163] op_sel_hi:[1,0]
	v_mul_f32_e32 v67, v71, v71
	v_mul_f32_e32 v69, v69, v69
	v_mul_f32_e32 v71, v159, v159
	v_mul_f32_e32 v157, v157, v157
	v_fmac_f32_e32 v67, v70, v70
	v_fmac_f32_e32 v69, v68, v68
	v_fmac_f32_e32 v71, v158, v158
	v_fmac_f32_e32 v157, v156, v156
	v_add_f32_e32 v67, v67, v69
	v_add_f32_e32 v68, v71, v157
	v_add_f32_e32 v67, v67, v68
	ds_bpermute_b32 v68, v197, v67
	s_waitcnt lgkmcnt(0)
	v_add_f32_e32 v67, v67, v68
	ds_bpermute_b32 v68, v198, v67
	s_and_saveexec_b64 s[36:37], s[6:7]
	s_cbranch_execz .LBB0_1354
	s_waitcnt lgkmcnt(0)
	v_add_f32_e32 v67, v67, v68
	ds_write_b32 v66, v67 offset:2560
.LBB0_1354:
	s_or_b64 exec, exec, s[36:37]
	s_nop 2
	v_mov_b32_e32 v64, v245
	v_fmamk_f32 v64, v64, 0x3b800000, v189
	v_rsq_f32_e32 v160, v64
	s_nop 0
	v_pk_mul_f32 v[64:65], v[14:15], v[160:161] op_sel_hi:[1,0]
	s_waitcnt lgkmcnt(0)
	v_pk_mul_f32 v[68:69], v[12:13], v[160:161] op_sel_hi:[1,0]
	v_pk_mul_f32 v[70:71], v[10:11], v[160:161] op_sel_hi:[1,0]
	v_pk_mul_f32 v[156:157], v[8:9], v[160:161] op_sel_hi:[1,0]
	v_mul_f32_e32 v67, v69, v69
	v_mul_f32_e32 v65, v65, v65
	v_mul_f32_e32 v69, v157, v157
	v_mul_f32_e32 v71, v71, v71
	v_fmac_f32_e32 v67, v68, v68
	v_fmac_f32_e32 v65, v64, v64
	v_fmac_f32_e32 v69, v156, v156
	v_fmac_f32_e32 v71, v70, v70
	v_add_f32_e32 v64, v67, v65
	v_add_f32_e32 v65, v69, v71
	v_add_f32_e32 v64, v64, v65
	ds_bpermute_b32 v65, v197, v64
	s_waitcnt lgkmcnt(0)
	v_add_f32_e32 v64, v64, v65
	ds_bpermute_b32 v65, v198, v64
	s_and_saveexec_b64 s[36:37], s[6:7]
	s_cbranch_execz .LBB0_1356
	s_waitcnt lgkmcnt(0)
	v_add_f32_e32 v64, v64, v65
	ds_write_b32 v66, v64 offset:2816
